# on top of nt residual loads/stores: removed the back-to-back s_setprio 0/1 pairs between the two 16-MFMA groups of every GEMM phase
# baseline (speedup 1.0000x reference)
; #define PG8_STAGE(bufoff, gbase, voff) do { _Pragma("unroll") for (int _i = 0; _i < 2; ++_i) \
;         __builtin_amdgcn_global_load_lds((const unsigned*)((const char*)(gbase) + (voff)[_i]), (PG8_LAS unsigned*)(lds + (bufoff) + ldsw + _i * (8 * USTR)), 16, 0, 0); } while (0)
; #define PG8_LDA(dst, b, h) do { _Pragma("unroll") for (int m = 0; m < 4; ++m) _Pragma("unroll") for (int k = 0; k < 2; ++k) dst[m][k] = *(const PG8_LAS bf16x8*)(lds + PG8_SA(b, h) + aoff + m * (2 * USTR) + k * 64); } while (0)
; #define PG8_LDB(dst, b, h) do { _Pragma("unroll") for (int n = 0; n < 2; ++n) _Pragma("unroll") for (int k = 0; k < 2; ++k) dst[n][k] = *(const PG8_LAS bf16x8*)(lds + PG8_SB(b, h) + boff + n * (2 * USTR) + k * 64); } while (0)
; #define PG8_MMA(ai, bj, At, Bt) do { __builtin_amdgcn_s_setprio(1); _Pragma("unroll") for (int m = 0; m < 4; ++m) _Pragma("unroll") for (int n = 0; n < 2; ++n) _Pragma("unroll") for (int k = 0; k < 2; ++k) \
;         acc[ai][bj][m][n] = __builtin_amdgcn_mfma_f32_16x16x32_bf16(Bt[n][k], At[m][k], acc[ai][bj][m][n], 0, 0, 0); __builtin_amdgcn_s_setprio(0); } while (0)
; #define PG8_WAIT_V(n) asm volatile("s_waitcnt vmcnt(" #n ")" ::: "memory")
; #define PG8_WAIT_L(n) asm volatile("s_waitcnt lgkmcnt(" #n ")" ::: "memory")
; #define PG8_BAR __builtin_amdgcn_s_barrier()
; #define PG8_SCHED __builtin_amdgcn_sched_barrier(0)
; template <class Epi, class Sched, bool ALIGN_EPI, bool SP2>
; __device__ __forceinline__ void gemm_phase(PG8_LAS unsigned char* lds, const Gemm g, const Sched& S, const Epi& E, int wid) {
;     ...
;             PG8_LDB(B0, 0, 0); PG8_LDB(B1, 0, 1); PG8_SCHED; PG8_LDA(At, 0, 0); PG8_STAGE(PG8_SA(1, 1), a1 + hstepA, voffA);
;             PG8_WAIT_V(8); PG8_WAIT_L(0); PG8_BAR; PG8_MMA(0, 0, At, B0); PG8_MMA(0, 1, At, B1); PG8_BAR; PG8_SCHED;
;             PG8_LDA(At, 0, 1); PG8_STAGE(PG8_SB(0, 0), b2, voffB); PG8_STAGE(PG8_SB(0, 1), b2 + hstepB, voffB); PG8_STAGE(PG8_SA(0, 0), a2, voffA);
;             PG8_WAIT_V(8); PG8_WAIT_L(0); PG8_BAR; PG8_MMA(1, 0, At, B0); PG8_MMA(1, 1, At, B1); PG8_BAR; PG8_SCHED;
.LBB0_150:
	s_add_u32 s40, s38, 0xfff80080
	s_addc_u32 s41, s39, -1
	s_add_i32 s95, 0, 0x11000
	s_cmp_eq_u32 s89, 12
	s_cselect_b32 s75, s26, s41
	s_cselect_b32 s74, s27, s40
	s_cselect_b32 s41, s23, s79
	s_cselect_b32 s40, s69, s78
	s_add_i32 s44, 0, 0x15400
	v_add_u32_e32 v60, s95, v216
	v_add_u32_e32 v156, s44, v216
	ds_read_b128 v[48:51], v60
	ds_read_b128 v[52:55], v60 offset:64
	ds_read_b128 v[56:59], v60 offset:2176
	ds_read_b128 v[60:63], v60 offset:2240
	ds_read_b128 v[144:147], v156
	ds_read_b128 v[148:151], v156 offset:64
	ds_read_b128 v[152:155], v156 offset:2176
	ds_read_b128 v[156:159], v156 offset:2240
	v_lshl_add_u64 v[198:199], s[38:39], 0, v[168:169]
	s_add_i32 m0, s0, 0xcc00
	ds_read_b128 v[172:175], v217
	ds_read_b128 v[176:179], v217 offset:64
	ds_read_b128 v[180:183], v217 offset:2176
	ds_read_b128 v[184:187], v217 offset:2240
	ds_read_b128 v[188:191], v217 offset:4352
	ds_read_b128 v[208:211], v217 offset:4416
	ds_read_b128 v[212:215], v217 offset:6528
	ds_read_b128 v[218:221], v217 offset:6592
	global_load_lds_dwordx4 v[198:199], off
	v_lshl_add_u64 v[198:199], s[38:39], 0, v[170:171]
	s_add_i32 m0, s0, 0xee00
	s_nop 0
	global_load_lds_dwordx4 v[198:199], off
	s_waitcnt vmcnt(8)
	s_waitcnt lgkmcnt(0)
	s_barrier
	s_setprio 1
	s_waitcnt lgkmcnt(0)
	v_mfma_f32_16x16x32_bf16 v[140:143], v[48:51], v[172:175], v[140:143]
	v_mfma_f32_16x16x32_bf16 v[136:139], v[56:59], v[172:175], v[136:139]
	v_mfma_f32_16x16x32_bf16 v[124:127], v[48:51], v[180:183], v[124:127]
	v_mfma_f32_16x16x32_bf16 v[120:123], v[56:59], v[180:183], v[120:123]
	v_mfma_f32_16x16x32_bf16 v[108:111], v[48:51], v[188:191], v[108:111]
	v_mfma_f32_16x16x32_bf16 v[104:107], v[56:59], v[188:191], v[104:107]
	v_mfma_f32_16x16x32_bf16 v[92:95], v[48:51], v[212:215], v[92:95]
	v_mfma_f32_16x16x32_bf16 v[88:91], v[56:59], v[212:215], v[88:91]
	v_mfma_f32_16x16x32_bf16 v[140:143], v[52:55], v[176:179], v[140:143]
	v_mfma_f32_16x16x32_bf16 v[136:139], v[60:63], v[176:179], v[136:139]
	v_mfma_f32_16x16x32_bf16 v[124:127], v[52:55], v[184:187], v[124:127]
	v_mfma_f32_16x16x32_bf16 v[120:123], v[60:63], v[184:187], v[120:123]
	v_mfma_f32_16x16x32_bf16 v[108:111], v[52:55], v[208:211], v[108:111]
	v_mfma_f32_16x16x32_bf16 v[104:107], v[60:63], v[208:211], v[104:107]
	v_mfma_f32_16x16x32_bf16 v[92:95], v[52:55], v[218:221], v[92:95]
	v_mfma_f32_16x16x32_bf16 v[88:91], v[60:63], v[218:221], v[88:91]
	v_mfma_f32_16x16x32_bf16 v[132:135], v[144:147], v[172:175], v[132:135]
	v_mfma_f32_16x16x32_bf16 v[128:131], v[152:155], v[172:175], v[128:131]
	v_mfma_f32_16x16x32_bf16 v[116:119], v[144:147], v[180:183], v[116:119]
	v_mfma_f32_16x16x32_bf16 v[112:115], v[152:155], v[180:183], v[112:115]
	v_mfma_f32_16x16x32_bf16 v[100:103], v[144:147], v[188:191], v[100:103]
	v_mfma_f32_16x16x32_bf16 v[96:99], v[152:155], v[188:191], v[96:99]
	v_mfma_f32_16x16x32_bf16 v[84:87], v[144:147], v[212:215], v[84:87]
	v_mfma_f32_16x16x32_bf16 v[80:83], v[152:155], v[212:215], v[80:83]
	v_mfma_f32_16x16x32_bf16 v[132:135], v[148:151], v[176:179], v[132:135]
	v_mfma_f32_16x16x32_bf16 v[128:131], v[156:159], v[176:179], v[128:131]
	v_mfma_f32_16x16x32_bf16 v[116:119], v[148:151], v[184:187], v[116:119]
	v_mfma_f32_16x16x32_bf16 v[112:115], v[156:159], v[184:187], v[112:115]
	v_mfma_f32_16x16x32_bf16 v[100:103], v[148:151], v[208:211], v[100:103]
	v_mfma_f32_16x16x32_bf16 v[96:99], v[156:159], v[208:211], v[96:99]
	v_mfma_f32_16x16x32_bf16 v[84:87], v[148:151], v[218:221], v[84:87]
	v_mfma_f32_16x16x32_bf16 v[80:83], v[156:159], v[218:221], v[80:83]
	s_setprio 0
	s_barrier
	s_add_i32 s45, s95, s33
	v_lshl_add_u64 v[198:199], s[40:41], 0, v[192:193]
	s_mov_b32 m0, s45
	ds_read_b128 v[172:175], v217 offset:17408
	ds_read_b128 v[176:179], v217 offset:17472
	ds_read_b128 v[180:183], v217 offset:19584
	ds_read_b128 v[184:187], v217 offset:19648
	ds_read_b128 v[188:191], v217 offset:21760
	ds_read_b128 v[208:211], v217 offset:21824
	ds_read_b128 v[212:215], v217 offset:23936
	ds_read_b128 v[218:221], v217 offset:24000
	global_load_lds_dwordx4 v[198:199], off
	s_add_i32 m0, s45, 0x2200
	s_add_u32 vcc_lo, s40, 0x40000
	v_lshl_add_u64 v[200:201], s[40:41], 0, v[160:161]
	s_addc_u32 vcc_hi, s41, 0
	s_add_i32 s44, s44, s33
	global_load_lds_dwordx4 v[200:201], off
	v_lshl_add_u64 v[222:223], vcc, 0, v[192:193]
	s_mov_b32 m0, s44
	v_lshl_add_u64 v[224:225], s[74:75], 0, v[162:163]
	global_load_lds_dwordx4 v[222:223], off
	v_lshl_add_u64 v[222:223], vcc, 0, v[160:161]
	s_add_i32 m0, s44, 0x2200
	s_nop 0
	global_load_lds_dwordx4 v[222:223], off
	v_lshl_add_u64 v[222:223], s[74:75], 0, v[164:165]
	s_mov_b32 m0, s0
	s_nop 0
	global_load_lds_dwordx4 v[222:223], off
	s_mov_b32 m0, s5
	s_nop 0
	global_load_lds_dwordx4 v[224:225], off
	s_waitcnt vmcnt(8)
	s_waitcnt lgkmcnt(0)
	s_barrier
; #define PG8_STAGE(bufoff, gbase, voff) do { _Pragma("unroll") for (int _i = 0; _i < 2; ++_i) \
;         __builtin_amdgcn_global_load_lds((const unsigned*)((const char*)(gbase) + (voff)[_i]), (PG8_LAS unsigned*)(lds + (bufoff) + ldsw + _i * (8 * USTR)), 16, 0, 0); } while (0)
; #define PG8_LDA(dst, b, h) do { _Pragma("unroll") for (int m = 0; m < 4; ++m) _Pragma("unroll") for (int k = 0; k < 2; ++k) dst[m][k] = *(const PG8_LAS bf16x8*)(lds + PG8_SA(b, h) + aoff + m * (2 * USTR) + k * 64); } while (0)
; #define PG8_LDB(dst, b, h) do { _Pragma("unroll") for (int n = 0; n < 2; ++n) _Pragma("unroll") for (int k = 0; k < 2; ++k) dst[n][k] = *(const PG8_LAS bf16x8*)(lds + PG8_SB(b, h) + boff + n * (2 * USTR) + k * 64); } while (0)
; #define PG8_MMA(ai, bj, At, Bt) do { __builtin_amdgcn_s_setprio(1); _Pragma("unroll") for (int m = 0; m < 4; ++m) _Pragma("unroll") for (int n = 0; n < 2; ++n) _Pragma("unroll") for (int k = 0; k < 2; ++k) \
;         acc[ai][bj][m][n] = __builtin_amdgcn_mfma_f32_16x16x32_bf16(Bt[n][k], At[m][k], acc[ai][bj][m][n], 0, 0, 0); __builtin_amdgcn_s_setprio(0); } while (0)
; #define PG8_WAIT_V(n) asm volatile("s_waitcnt vmcnt(" #n ")" ::: "memory")
; #define PG8_WAIT_L(n) asm volatile("s_waitcnt lgkmcnt(" #n ")" ::: "memory")
; #define PG8_BAR __builtin_amdgcn_s_barrier()
; #define PG8_SCHED __builtin_amdgcn_sched_barrier(0)
; template <class Epi, class Sched, bool ALIGN_EPI, bool SP2>
; __device__ __forceinline__ void gemm_phase(PG8_LAS unsigned char* lds, const Gemm g, const Sched& S, const Epi& E, int wid) {
;     ...
;             PG8_WAIT_V(8); PG8_WAIT_L(0); PG8_BAR; PG8_MMA(1, 0, At, B0); PG8_MMA(1, 1, At, B1); PG8_BAR; PG8_SCHED;
;             PG8_LDB(B0, 1, 0); PG8_LDB(B1, 1, 1); PG8_SCHED; PG8_LDA(At, 1, 0); PG8_STAGE(PG8_SA(0, 1), a2 + hstepA, voffA);
;             PG8_WAIT_V(8); PG8_WAIT_L(0); PG8_BAR; PG8_MMA(0, 0, At, B0); PG8_MMA(0, 1, At, B1); PG8_BAR; PG8_SCHED;
	s_setprio 1
	s_waitcnt lgkmcnt(0)
	v_mfma_f32_16x16x32_bf16 v[76:79], v[48:51], v[172:175], v[76:79]
	v_mfma_f32_16x16x32_bf16 v[72:75], v[56:59], v[172:175], v[72:75]
	v_mfma_f32_16x16x32_bf16 v[44:47], v[48:51], v[180:183], v[44:47]
	v_mfma_f32_16x16x32_bf16 v[40:43], v[56:59], v[180:183], v[40:43]
	v_mfma_f32_16x16x32_bf16 v[24:27], v[48:51], v[188:191], v[24:27]
	v_mfma_f32_16x16x32_bf16 v[28:31], v[56:59], v[188:191], v[28:31]
	v_mfma_f32_16x16x32_bf16 v[4:7], v[48:51], v[212:215], v[4:7]
	v_mfma_f32_16x16x32_bf16 v[12:15], v[56:59], v[212:215], v[12:15]
	v_mfma_f32_16x16x32_bf16 v[76:79], v[52:55], v[176:179], v[76:79]
	v_mfma_f32_16x16x32_bf16 v[72:75], v[60:63], v[176:179], v[72:75]
	v_mfma_f32_16x16x32_bf16 v[44:47], v[52:55], v[184:187], v[44:47]
	v_mfma_f32_16x16x32_bf16 v[40:43], v[60:63], v[184:187], v[40:43]
	v_mfma_f32_16x16x32_bf16 v[24:27], v[52:55], v[208:211], v[24:27]
	v_mfma_f32_16x16x32_bf16 v[28:31], v[60:63], v[208:211], v[28:31]
	v_mfma_f32_16x16x32_bf16 v[4:7], v[52:55], v[218:221], v[4:7]
	v_mfma_f32_16x16x32_bf16 v[12:15], v[60:63], v[218:221], v[12:15]
	v_mfma_f32_16x16x32_bf16 v[36:39], v[144:147], v[180:183], v[36:39]
	v_mfma_f32_16x16x32_bf16 v[32:35], v[152:155], v[180:183], v[32:35]
	v_mfma_f32_16x16x32_bf16 v[20:23], v[144:147], v[188:191], v[20:23]
	v_mfma_f32_16x16x32_bf16 v[16:19], v[152:155], v[188:191], v[16:19]
	v_mfma_f32_16x16x32_bf16 v[8:11], v[144:147], v[212:215], v[8:11]
	v_mfma_f32_16x16x32_bf16 v[0:3], v[152:155], v[212:215], v[0:3]
	v_mfma_f32_16x16x32_bf16 v[48:51], v[144:147], v[172:175], v[68:71]
	v_mfma_f32_16x16x32_bf16 v[52:55], v[152:155], v[172:175], v[64:67]
	v_mfma_f32_16x16x32_bf16 v[36:39], v[148:151], v[184:187], v[36:39]
	v_mfma_f32_16x16x32_bf16 v[32:35], v[156:159], v[184:187], v[32:35]
	v_mfma_f32_16x16x32_bf16 v[20:23], v[148:151], v[208:211], v[20:23]
	v_mfma_f32_16x16x32_bf16 v[16:19], v[156:159], v[208:211], v[16:19]
	v_mfma_f32_16x16x32_bf16 v[8:11], v[148:151], v[218:221], v[8:11]
	v_mfma_f32_16x16x32_bf16 v[0:3], v[156:159], v[218:221], v[0:3]
	v_mfma_f32_16x16x32_bf16 v[48:51], v[148:151], v[176:179], v[48:51]
	v_mfma_f32_16x16x32_bf16 v[52:55], v[156:159], v[176:179], v[52:55]
	s_setprio 0
	s_barrier
	s_add_i32 s44, 0, 0x19800
	s_add_i32 s45, 0, 0x1dc00
	v_add_u32_e32 v68, s44, v216
	v_add_u32_e32 v156, s45, v216
	ds_read_b128 v[56:59], v68
	ds_read_b128 v[60:63], v68 offset:64
	ds_read_b128 v[64:67], v68 offset:2176
	ds_read_b128 v[68:71], v68 offset:2240
	ds_read_b128 v[144:147], v156
	ds_read_b128 v[148:151], v156 offset:64
	ds_read_b128 v[152:155], v156 offset:2176
	ds_read_b128 v[156:159], v156 offset:2240
	s_add_u32 s74, s74, 0x80000
	s_addc_u32 s75, s75, 0
	s_mov_b32 m0, s29
	v_lshl_add_u64 v[226:227], s[74:75], 0, v[164:165]
	ds_read_b128 v[172:175], v217 offset:34816
	ds_read_b128 v[176:179], v217 offset:34880
	ds_read_b128 v[180:183], v217 offset:36992
	ds_read_b128 v[184:187], v217 offset:37056
	ds_read_b128 v[188:191], v217 offset:39168
	ds_read_b128 v[208:211], v217 offset:39232
	ds_read_b128 v[212:215], v217 offset:41344
	ds_read_b128 v[218:221], v217 offset:41408
	global_load_lds_dwordx4 v[226:227], off
	v_lshl_add_u64 v[226:227], s[74:75], 0, v[162:163]
	s_mov_b32 m0, s56
	s_nop 0
	global_load_lds_dwordx4 v[226:227], off
	s_waitcnt vmcnt(8)
	s_waitcnt lgkmcnt(0)
	s_barrier
	s_setprio 1
	s_waitcnt lgkmcnt(0)
	v_mfma_f32_16x16x32_bf16 v[140:143], v[56:59], v[172:175], v[140:143]
	v_mfma_f32_16x16x32_bf16 v[136:139], v[64:67], v[172:175], v[136:139]
	v_mfma_f32_16x16x32_bf16 v[124:127], v[56:59], v[180:183], v[124:127]
	v_mfma_f32_16x16x32_bf16 v[120:123], v[64:67], v[180:183], v[120:123]
	v_mfma_f32_16x16x32_bf16 v[108:111], v[56:59], v[188:191], v[108:111]
	v_mfma_f32_16x16x32_bf16 v[104:107], v[64:67], v[188:191], v[104:107]
	v_mfma_f32_16x16x32_bf16 v[92:95], v[56:59], v[212:215], v[92:95]
	v_mfma_f32_16x16x32_bf16 v[88:91], v[64:67], v[212:215], v[88:91]
	v_mfma_f32_16x16x32_bf16 v[140:143], v[60:63], v[176:179], v[140:143]
	v_mfma_f32_16x16x32_bf16 v[136:139], v[68:71], v[176:179], v[136:139]
	v_mfma_f32_16x16x32_bf16 v[124:127], v[60:63], v[184:187], v[124:127]
	v_mfma_f32_16x16x32_bf16 v[120:123], v[68:71], v[184:187], v[120:123]
	v_mfma_f32_16x16x32_bf16 v[108:111], v[60:63], v[208:211], v[108:111]
	v_mfma_f32_16x16x32_bf16 v[104:107], v[68:71], v[208:211], v[104:107]
	v_mfma_f32_16x16x32_bf16 v[92:95], v[60:63], v[218:221], v[92:95]
	v_mfma_f32_16x16x32_bf16 v[88:91], v[68:71], v[218:221], v[88:91]
	v_mfma_f32_16x16x32_bf16 v[132:135], v[144:147], v[172:175], v[132:135]
	v_mfma_f32_16x16x32_bf16 v[128:131], v[152:155], v[172:175], v[128:131]
	v_mfma_f32_16x16x32_bf16 v[116:119], v[144:147], v[180:183], v[116:119]
	v_mfma_f32_16x16x32_bf16 v[112:115], v[152:155], v[180:183], v[112:115]
	v_mfma_f32_16x16x32_bf16 v[100:103], v[144:147], v[188:191], v[100:103]
	v_mfma_f32_16x16x32_bf16 v[96:99], v[152:155], v[188:191], v[96:99]
	v_mfma_f32_16x16x32_bf16 v[84:87], v[144:147], v[212:215], v[84:87]
	v_mfma_f32_16x16x32_bf16 v[80:83], v[152:155], v[212:215], v[80:83]
	v_mfma_f32_16x16x32_bf16 v[132:135], v[148:151], v[176:179], v[132:135]
	v_mfma_f32_16x16x32_bf16 v[128:131], v[156:159], v[176:179], v[128:131]
	v_mfma_f32_16x16x32_bf16 v[116:119], v[148:151], v[184:187], v[116:119]
	v_mfma_f32_16x16x32_bf16 v[112:115], v[156:159], v[184:187], v[112:115]
	v_mfma_f32_16x16x32_bf16 v[100:103], v[148:151], v[208:211], v[100:103]
	v_mfma_f32_16x16x32_bf16 v[96:99], v[156:159], v[208:211], v[96:99]
	v_mfma_f32_16x16x32_bf16 v[84:87], v[148:151], v[218:221], v[84:87]
	v_mfma_f32_16x16x32_bf16 v[80:83], v[156:159], v[218:221], v[80:83]
	s_setprio 0
	s_barrier
; #define PG8_STAGE(bufoff, gbase, voff) do { _Pragma("unroll") for (int _i = 0; _i < 2; ++_i) \
;         __builtin_amdgcn_global_load_lds((const unsigned*)((const char*)(gbase) + (voff)[_i]), (PG8_LAS unsigned*)(lds + (bufoff) + ldsw + _i * (8 * USTR)), 16, 0, 0); } while (0)
; #define PG8_LDA(dst, b, h) do { _Pragma("unroll") for (int m = 0; m < 4; ++m) _Pragma("unroll") for (int k = 0; k < 2; ++k) dst[m][k] = *(const PG8_LAS bf16x8*)(lds + PG8_SA(b, h) + aoff + m * (2 * USTR) + k * 64); } while (0)
; #define PG8_MMA(ai, bj, At, Bt) do { __builtin_amdgcn_s_setprio(1); _Pragma("unroll") for (int m = 0; m < 4; ++m) _Pragma("unroll") for (int n = 0; n < 2; ++n) _Pragma("unroll") for (int k = 0; k < 2; ++k) \
;         acc[ai][bj][m][n] = __builtin_amdgcn_mfma_f32_16x16x32_bf16(Bt[n][k], At[m][k], acc[ai][bj][m][n], 0, 0, 0); __builtin_amdgcn_s_setprio(0); } while (0)
; #define PG8_WAIT_V(n) asm volatile("s_waitcnt vmcnt(" #n ")" ::: "memory")
; #define PG8_WAIT_L(n) asm volatile("s_waitcnt lgkmcnt(" #n ")" ::: "memory")
; #define PG8_BAR __builtin_amdgcn_s_barrier()
; #define PG8_SCHED __builtin_amdgcn_sched_barrier(0)
; template <class Epi, class Sched, bool ALIGN_EPI, bool SP2>
; __device__ __forceinline__ void gemm_phase(PG8_LAS unsigned char* lds, const Gemm g, const Sched& S, const Epi& E, int wid) {
;     ...
;             PG8_LDA(At, 1, 1); PG8_STAGE(PG8_SB(1, 0), b3, voffB); PG8_STAGE(PG8_SB(1, 1), b3 + hstepB, voffB); PG8_STAGE(PG8_SA(1, 0), a3, voffA);
;             PG8_WAIT_V(8); PG8_WAIT_L(0); PG8_BAR; PG8_MMA(1, 0, At, B0); PG8_MMA(1, 1, At, B1); PG8_BAR; PG8_SCHED;
	s_add_i32 s44, s44, s33
	v_lshl_add_u64 v[198:199], v[198:199], 0, s[6:7]
	s_mov_b32 m0, s44
	ds_read_b128 v[172:175], v217 offset:52224
	ds_read_b128 v[176:179], v217 offset:52288
	ds_read_b128 v[180:183], v217 offset:54400
	ds_read_b128 v[184:187], v217 offset:54464
	ds_read_b128 v[188:191], v217 offset:56576
	ds_read_b128 v[208:211], v217 offset:56640
	ds_read_b128 v[212:215], v217 offset:58752
	ds_read_b128 v[218:221], v217 offset:58816
	global_load_lds_dwordx4 v[198:199], off
	s_add_i32 m0, s44, 0x2200
	s_add_u32 s40, s40, 0x40080
	v_lshl_add_u64 v[198:199], v[200:201], 0, s[6:7]
	s_addc_u32 s41, s41, 0
	s_add_i32 s44, s45, s33
	global_load_lds_dwordx4 v[198:199], off
	v_lshl_add_u64 v[198:199], s[40:41], 0, v[192:193]
	s_mov_b32 m0, s44
	s_nop 0
	global_load_lds_dwordx4 v[198:199], off
	v_lshl_add_u64 v[198:199], s[40:41], 0, v[160:161]
	s_add_i32 m0, s44, 0x2200
	s_nop 0
	global_load_lds_dwordx4 v[198:199], off
	v_lshl_add_u64 v[198:199], v[222:223], 0, s[6:7]
	s_mov_b32 m0, s57
	s_nop 0
	global_load_lds_dwordx4 v[198:199], off
	v_lshl_add_u64 v[198:199], v[224:225], 0, s[6:7]
	s_mov_b32 m0, s76
	s_nop 0
	global_load_lds_dwordx4 v[198:199], off
	s_waitcnt vmcnt(8)
	s_waitcnt lgkmcnt(0)
	s_barrier
	s_setprio 1
	s_waitcnt lgkmcnt(0)
	v_mfma_f32_16x16x32_bf16 v[76:79], v[56:59], v[172:175], v[76:79]
	v_mfma_f32_16x16x32_bf16 v[72:75], v[64:67], v[172:175], v[72:75]
	v_mfma_f32_16x16x32_bf16 v[44:47], v[56:59], v[180:183], v[44:47]
	v_mfma_f32_16x16x32_bf16 v[40:43], v[64:67], v[180:183], v[40:43]
	v_mfma_f32_16x16x32_bf16 v[24:27], v[56:59], v[188:191], v[24:27]
	v_mfma_f32_16x16x32_bf16 v[28:31], v[64:67], v[188:191], v[28:31]
	v_mfma_f32_16x16x32_bf16 v[4:7], v[56:59], v[212:215], v[4:7]
	v_mfma_f32_16x16x32_bf16 v[12:15], v[64:67], v[212:215], v[12:15]
	v_mfma_f32_16x16x32_bf16 v[76:79], v[60:63], v[176:179], v[76:79]
	v_mfma_f32_16x16x32_bf16 v[72:75], v[68:71], v[176:179], v[72:75]
	v_mfma_f32_16x16x32_bf16 v[44:47], v[60:63], v[184:187], v[44:47]
	v_mfma_f32_16x16x32_bf16 v[40:43], v[68:71], v[184:187], v[40:43]
	v_mfma_f32_16x16x32_bf16 v[24:27], v[60:63], v[208:211], v[24:27]
	v_mfma_f32_16x16x32_bf16 v[28:31], v[68:71], v[208:211], v[28:31]
	v_mfma_f32_16x16x32_bf16 v[4:7], v[60:63], v[218:221], v[4:7]
	v_mfma_f32_16x16x32_bf16 v[12:15], v[68:71], v[218:221], v[12:15]
	v_mfma_f32_16x16x32_bf16 v[48:51], v[144:147], v[172:175], v[48:51]
	v_mfma_f32_16x16x32_bf16 v[68:71], v[148:151], v[176:179], v[48:51]
	v_mfma_f32_16x16x32_bf16 v[48:51], v[152:155], v[172:175], v[52:55]
	v_mfma_f32_16x16x32_bf16 v[36:39], v[144:147], v[180:183], v[36:39]
	v_mfma_f32_16x16x32_bf16 v[32:35], v[152:155], v[180:183], v[32:35]
	v_mfma_f32_16x16x32_bf16 v[20:23], v[144:147], v[188:191], v[20:23]
	v_mfma_f32_16x16x32_bf16 v[16:19], v[152:155], v[188:191], v[16:19]
	v_mfma_f32_16x16x32_bf16 v[8:11], v[144:147], v[212:215], v[8:11]
	v_mfma_f32_16x16x32_bf16 v[0:3], v[152:155], v[212:215], v[0:3]
	v_mfma_f32_16x16x32_bf16 v[64:67], v[156:159], v[176:179], v[48:51]
	v_mfma_f32_16x16x32_bf16 v[36:39], v[148:151], v[184:187], v[36:39]
	v_mfma_f32_16x16x32_bf16 v[32:35], v[156:159], v[184:187], v[32:35]
	v_mfma_f32_16x16x32_bf16 v[20:23], v[148:151], v[208:211], v[20:23]
	v_mfma_f32_16x16x32_bf16 v[16:19], v[156:159], v[208:211], v[16:19]
	v_mfma_f32_16x16x32_bf16 v[8:11], v[148:151], v[218:221], v[8:11]
	v_mfma_f32_16x16x32_bf16 v[0:3], v[156:159], v[218:221], v[0:3]
	s_setprio 0
	s_barrier
	s_add_i32 s89, s89, 2
	s_add_u32 s38, s38, 0x100
	s_addc_u32 s39, s39, 0
	s_add_u32 s78, s78, 0x100
	s_addc_u32 s79, s79, 0
	s_cmp_gt_u32 s89, 13
	s_cbranch_scc0 .LBB0_150
	s_and_b64 vcc, exec, s[20:21]
	s_cbranch_vccz .LBB0_153
	s_barrier

; #define PG8_STAGE(bufoff, gbase, voff) do { _Pragma("unroll") for (int _i = 0; _i < 2; ++_i) \
;         __builtin_amdgcn_global_load_lds((const unsigned*)((const char*)(gbase) + (voff)[_i]), (PG8_LAS unsigned*)(lds + (bufoff) + ldsw + _i * (8 * USTR)), 16, 0, 0); } while (0)
; #define PG8_LDA(dst, b, h) do { _Pragma("unroll") for (int m = 0; m < 4; ++m) _Pragma("unroll") for (int k = 0; k < 2; ++k) dst[m][k] = *(const PG8_LAS bf16x8*)(lds + PG8_SA(b, h) + aoff + m * (2 * USTR) + k * 64); } while (0)
; #define PG8_LDB(dst, b, h) do { _Pragma("unroll") for (int n = 0; n < 2; ++n) _Pragma("unroll") for (int k = 0; k < 2; ++k) dst[n][k] = *(const PG8_LAS bf16x8*)(lds + PG8_SB(b, h) + boff + n * (2 * USTR) + k * 64); } while (0)
; #define PG8_MMA(ai, bj, At, Bt) do { __builtin_amdgcn_s_setprio(1); _Pragma("unroll") for (int m = 0; m < 4; ++m) _Pragma("unroll") for (int n = 0; n < 2; ++n) _Pragma("unroll") for (int k = 0; k < 2; ++k) \
;         acc[ai][bj][m][n] = __builtin_amdgcn_mfma_f32_16x16x32_bf16(Bt[n][k], At[m][k], acc[ai][bj][m][n], 0, 0, 0); __builtin_amdgcn_s_setprio(0); } while (0)
; #define PG8_WAIT_V(n) asm volatile("s_waitcnt vmcnt(" #n ")" ::: "memory")
; #define PG8_WAIT_L(n) asm volatile("s_waitcnt lgkmcnt(" #n ")" ::: "memory")
; #define PG8_BAR __builtin_amdgcn_s_barrier()
; #define PG8_SCHED __builtin_amdgcn_sched_barrier(0)
; template <class Epi, class Sched, bool ALIGN_EPI, bool SP2>
; __device__ __forceinline__ void gemm_phase(PG8_LAS unsigned char* lds, const Gemm g, const Sched& S, const Epi& E, int wid) {
;     ...
;             PG8_LDB(B0, 0, 0); PG8_LDB(B1, 0, 1); PG8_SCHED; PG8_LDA(At, 0, 0); PG8_STAGE(PG8_SA(1, 1), a1 + hstepA, voffA);
;             PG8_WAIT_V(8); PG8_WAIT_L(0); PG8_BAR; PG8_MMA(0, 0, At, B0); PG8_MMA(0, 1, At, B1); PG8_BAR; PG8_SCHED;
;             PG8_LDA(At, 0, 1); PG8_STAGE(PG8_SB(0, 0), b2, voffB); PG8_STAGE(PG8_SB(0, 1), b2 + hstepB, voffB); PG8_STAGE(PG8_SA(0, 0), a2, voffA);
;             PG8_WAIT_V(8); PG8_WAIT_L(0); PG8_BAR; PG8_MMA(1, 0, At, B0); PG8_MMA(1, 1, At, B1); PG8_BAR; PG8_SCHED;
.LBB0_290:
	s_add_u32 s40, s38, 0xfff50080
	s_addc_u32 s41, s39, -1
	s_add_i32 s69, 0, 0x11000
	s_cmp_eq_u32 s68, 40
	s_cselect_b32 s43, s23, s41
	s_cselect_b32 s42, s22, s40
	s_cselect_b32 s41, s45, s27
	s_cselect_b32 s40, s44, s26
	s_add_i32 s76, 0, 0x15400
	v_add_u32_e32 v52, s69, v197
	v_add_u32_e32 v156, s76, v197
	ds_read_b128 v[40:43], v52
	ds_read_b128 v[44:47], v52 offset:64
	ds_read_b128 v[48:51], v52 offset:2176
	ds_read_b128 v[52:55], v52 offset:2240
	ds_read_b128 v[144:147], v156
	ds_read_b128 v[148:151], v156 offset:64
	ds_read_b128 v[152:155], v156 offset:2176
	ds_read_b128 v[156:159], v156 offset:2240
	v_lshl_add_u64 v[198:199], s[38:39], 0, v[212:213]
	s_add_i32 m0, s0, 0xcc00
	ds_read_b128 v[160:163], v241
	ds_read_b128 v[164:167], v241 offset:64
	ds_read_b128 v[168:171], v241 offset:2176
	ds_read_b128 v[172:175], v241 offset:2240
	ds_read_b128 v[176:179], v241 offset:4352
	ds_read_b128 v[180:183], v241 offset:4416
	ds_read_b128 v[184:187], v241 offset:6528
	ds_read_b128 v[188:191], v241 offset:6592
	global_load_lds_dwordx4 v[198:199], off
	v_lshl_add_u64 v[198:199], s[38:39], 0, v[214:215]
	s_add_i32 m0, s0, 0xee00
	s_nop 0
	global_load_lds_dwordx4 v[198:199], off
	s_waitcnt vmcnt(8)
	s_waitcnt lgkmcnt(0)
	s_barrier
	s_setprio 1
	s_waitcnt lgkmcnt(0)
	v_mfma_f32_16x16x32_bf16 v[132:135], v[40:43], v[160:163], v[132:135]
	v_mfma_f32_16x16x32_bf16 v[128:131], v[48:51], v[160:163], v[128:131]
	v_mfma_f32_16x16x32_bf16 v[124:127], v[40:43], v[168:171], v[124:127]
	v_mfma_f32_16x16x32_bf16 v[120:123], v[48:51], v[168:171], v[120:123]
	v_mfma_f32_16x16x32_bf16 v[108:111], v[40:43], v[176:179], v[108:111]
	v_mfma_f32_16x16x32_bf16 v[104:107], v[48:51], v[176:179], v[104:107]
	v_mfma_f32_16x16x32_bf16 v[92:95], v[40:43], v[184:187], v[92:95]
	v_mfma_f32_16x16x32_bf16 v[88:91], v[48:51], v[184:187], v[88:91]
	v_mfma_f32_16x16x32_bf16 v[132:135], v[44:47], v[164:167], v[132:135]
	v_mfma_f32_16x16x32_bf16 v[128:131], v[52:55], v[164:167], v[128:131]
	v_mfma_f32_16x16x32_bf16 v[124:127], v[44:47], v[172:175], v[124:127]
	v_mfma_f32_16x16x32_bf16 v[120:123], v[52:55], v[172:175], v[120:123]
	v_mfma_f32_16x16x32_bf16 v[108:111], v[44:47], v[180:183], v[108:111]
	v_mfma_f32_16x16x32_bf16 v[104:107], v[52:55], v[180:183], v[104:107]
	v_mfma_f32_16x16x32_bf16 v[92:95], v[44:47], v[188:191], v[92:95]
	v_mfma_f32_16x16x32_bf16 v[88:91], v[52:55], v[188:191], v[88:91]
	v_mfma_f32_16x16x32_bf16 v[140:143], v[144:147], v[160:163], v[140:143]
	v_mfma_f32_16x16x32_bf16 v[136:139], v[152:155], v[160:163], v[136:139]
	v_mfma_f32_16x16x32_bf16 v[116:119], v[144:147], v[168:171], v[116:119]
	v_mfma_f32_16x16x32_bf16 v[112:115], v[152:155], v[168:171], v[112:115]
	v_mfma_f32_16x16x32_bf16 v[100:103], v[144:147], v[176:179], v[100:103]
	v_mfma_f32_16x16x32_bf16 v[96:99], v[152:155], v[176:179], v[96:99]
	v_mfma_f32_16x16x32_bf16 v[84:87], v[144:147], v[184:187], v[84:87]
	v_mfma_f32_16x16x32_bf16 v[80:83], v[152:155], v[184:187], v[80:83]
	v_mfma_f32_16x16x32_bf16 v[140:143], v[148:151], v[164:167], v[140:143]
	v_mfma_f32_16x16x32_bf16 v[136:139], v[156:159], v[164:167], v[136:139]
	v_mfma_f32_16x16x32_bf16 v[116:119], v[148:151], v[172:175], v[116:119]
	v_mfma_f32_16x16x32_bf16 v[112:115], v[156:159], v[172:175], v[112:115]
	v_mfma_f32_16x16x32_bf16 v[100:103], v[148:151], v[180:183], v[100:103]
	v_mfma_f32_16x16x32_bf16 v[96:99], v[156:159], v[180:183], v[96:99]
	v_mfma_f32_16x16x32_bf16 v[84:87], v[148:151], v[188:191], v[84:87]
	v_mfma_f32_16x16x32_bf16 v[80:83], v[156:159], v[188:191], v[80:83]
	s_setprio 0
	s_barrier
	s_add_i32 s69, s69, s33
	v_lshl_add_u64 v[198:199], s[40:41], 0, v[208:209]
	s_mov_b32 m0, s69
	ds_read_b128 v[160:163], v241 offset:17408
	ds_read_b128 v[164:167], v241 offset:17472
	ds_read_b128 v[168:171], v241 offset:19584
	ds_read_b128 v[172:175], v241 offset:19648
	ds_read_b128 v[176:179], v241 offset:21760
	ds_read_b128 v[180:183], v241 offset:21824
	ds_read_b128 v[184:187], v241 offset:23936
	ds_read_b128 v[188:191], v241 offset:24000
	global_load_lds_dwordx4 v[198:199], off
	s_add_i32 m0, s69, 0x2200
	s_add_u32 s74, s40, 0xb0000
	v_lshl_add_u64 v[200:201], s[40:41], 0, v[210:211]
	s_addc_u32 s75, s41, 0
	s_add_i32 s69, s76, s33
	global_load_lds_dwordx4 v[200:201], off
	v_lshl_add_u64 v[216:217], s[74:75], 0, v[208:209]
	s_mov_b32 m0, s69
	v_lshl_add_u64 v[218:219], s[42:43], 0, v[210:211]
	global_load_lds_dwordx4 v[216:217], off
	v_lshl_add_u64 v[216:217], s[74:75], 0, v[210:211]
	s_add_i32 m0, s69, 0x2200
	s_nop 0
	global_load_lds_dwordx4 v[216:217], off
	v_lshl_add_u64 v[216:217], s[42:43], 0, v[208:209]
	s_mov_b32 m0, s0
	s_nop 0
	global_load_lds_dwordx4 v[216:217], off
	s_mov_b32 m0, s5
	s_nop 0
	global_load_lds_dwordx4 v[218:219], off
	s_waitcnt vmcnt(8)
	s_waitcnt lgkmcnt(0)
	s_barrier
; #define PG8_STAGE(bufoff, gbase, voff) do { _Pragma("unroll") for (int _i = 0; _i < 2; ++_i) \
;         __builtin_amdgcn_global_load_lds((const unsigned*)((const char*)(gbase) + (voff)[_i]), (PG8_LAS unsigned*)(lds + (bufoff) + ldsw + _i * (8 * USTR)), 16, 0, 0); } while (0)
; #define PG8_LDA(dst, b, h) do { _Pragma("unroll") for (int m = 0; m < 4; ++m) _Pragma("unroll") for (int k = 0; k < 2; ++k) dst[m][k] = *(const PG8_LAS bf16x8*)(lds + PG8_SA(b, h) + aoff + m * (2 * USTR) + k * 64); } while (0)
; #define PG8_LDB(dst, b, h) do { _Pragma("unroll") for (int n = 0; n < 2; ++n) _Pragma("unroll") for (int k = 0; k < 2; ++k) dst[n][k] = *(const PG8_LAS bf16x8*)(lds + PG8_SB(b, h) + boff + n * (2 * USTR) + k * 64); } while (0)
; #define PG8_MMA(ai, bj, At, Bt) do { __builtin_amdgcn_s_setprio(1); _Pragma("unroll") for (int m = 0; m < 4; ++m) _Pragma("unroll") for (int n = 0; n < 2; ++n) _Pragma("unroll") for (int k = 0; k < 2; ++k) \
;         acc[ai][bj][m][n] = __builtin_amdgcn_mfma_f32_16x16x32_bf16(Bt[n][k], At[m][k], acc[ai][bj][m][n], 0, 0, 0); __builtin_amdgcn_s_setprio(0); } while (0)
; #define PG8_WAIT_V(n) asm volatile("s_waitcnt vmcnt(" #n ")" ::: "memory")
; #define PG8_WAIT_L(n) asm volatile("s_waitcnt lgkmcnt(" #n ")" ::: "memory")
; #define PG8_BAR __builtin_amdgcn_s_barrier()
; #define PG8_SCHED __builtin_amdgcn_sched_barrier(0)
; template <class Epi, class Sched, bool ALIGN_EPI, bool SP2>
; __device__ __forceinline__ void gemm_phase(PG8_LAS unsigned char* lds, const Gemm g, const Sched& S, const Epi& E, int wid) {
;     ...
;             PG8_WAIT_V(8); PG8_WAIT_L(0); PG8_BAR; PG8_MMA(1, 0, At, B0); PG8_MMA(1, 1, At, B1); PG8_BAR; PG8_SCHED;
;             PG8_LDB(B0, 1, 0); PG8_LDB(B1, 1, 1); PG8_SCHED; PG8_LDA(At, 1, 0); PG8_STAGE(PG8_SA(0, 1), a2 + hstepA, voffA);
;             PG8_WAIT_V(8); PG8_WAIT_L(0); PG8_BAR; PG8_MMA(0, 0, At, B0); PG8_MMA(0, 1, At, B1); PG8_BAR; PG8_SCHED;
	s_setprio 1
	s_waitcnt lgkmcnt(0)
	v_mfma_f32_16x16x32_bf16 v[76:79], v[40:43], v[160:163], v[76:79]
	v_mfma_f32_16x16x32_bf16 v[72:75], v[48:51], v[160:163], v[72:75]
	v_mfma_f32_16x16x32_bf16 v[60:63], v[40:43], v[168:171], v[60:63]
	v_mfma_f32_16x16x32_bf16 v[56:59], v[48:51], v[168:171], v[56:59]
	v_mfma_f32_16x16x32_bf16 v[24:27], v[40:43], v[176:179], v[24:27]
	v_mfma_f32_16x16x32_bf16 v[28:31], v[48:51], v[176:179], v[28:31]
	v_mfma_f32_16x16x32_bf16 v[8:11], v[40:43], v[184:187], v[8:11]
	v_mfma_f32_16x16x32_bf16 v[12:15], v[48:51], v[184:187], v[12:15]
	v_mfma_f32_16x16x32_bf16 v[76:79], v[44:47], v[164:167], v[76:79]
	v_mfma_f32_16x16x32_bf16 v[72:75], v[52:55], v[164:167], v[72:75]
	v_mfma_f32_16x16x32_bf16 v[60:63], v[44:47], v[172:175], v[60:63]
	v_mfma_f32_16x16x32_bf16 v[56:59], v[52:55], v[172:175], v[56:59]
	v_mfma_f32_16x16x32_bf16 v[24:27], v[44:47], v[180:183], v[24:27]
	v_mfma_f32_16x16x32_bf16 v[28:31], v[52:55], v[180:183], v[28:31]
	v_mfma_f32_16x16x32_bf16 v[8:11], v[44:47], v[188:191], v[8:11]
	v_mfma_f32_16x16x32_bf16 v[12:15], v[52:55], v[188:191], v[12:15]
	v_mfma_f32_16x16x32_bf16 v[36:39], v[144:147], v[168:171], v[36:39]
	v_mfma_f32_16x16x32_bf16 v[32:35], v[152:155], v[168:171], v[32:35]
	v_mfma_f32_16x16x32_bf16 v[20:23], v[144:147], v[176:179], v[20:23]
	v_mfma_f32_16x16x32_bf16 v[16:19], v[152:155], v[176:179], v[16:19]
	v_mfma_f32_16x16x32_bf16 v[4:7], v[144:147], v[184:187], v[4:7]
	v_mfma_f32_16x16x32_bf16 v[0:3], v[152:155], v[184:187], v[0:3]
	v_mfma_f32_16x16x32_bf16 v[40:43], v[144:147], v[160:163], v[68:71]
	v_mfma_f32_16x16x32_bf16 v[44:47], v[152:155], v[160:163], v[64:67]
	v_mfma_f32_16x16x32_bf16 v[36:39], v[148:151], v[172:175], v[36:39]
	v_mfma_f32_16x16x32_bf16 v[32:35], v[156:159], v[172:175], v[32:35]
	v_mfma_f32_16x16x32_bf16 v[20:23], v[148:151], v[180:183], v[20:23]
	v_mfma_f32_16x16x32_bf16 v[16:19], v[156:159], v[180:183], v[16:19]
	v_mfma_f32_16x16x32_bf16 v[4:7], v[148:151], v[188:191], v[4:7]
	v_mfma_f32_16x16x32_bf16 v[0:3], v[156:159], v[188:191], v[0:3]
	v_mfma_f32_16x16x32_bf16 v[40:43], v[148:151], v[164:167], v[40:43]
	v_mfma_f32_16x16x32_bf16 v[44:47], v[156:159], v[164:167], v[44:47]
	s_setprio 0
	s_barrier
	s_add_i32 s69, 0, 0x19800
	s_add_i32 s74, 0, 0x1dc00
	v_add_u32_e32 v68, s69, v197
	v_add_u32_e32 v156, s74, v197
	ds_read_b128 v[48:51], v68
	ds_read_b128 v[52:55], v68 offset:64
	ds_read_b128 v[64:67], v68 offset:2176
	ds_read_b128 v[68:71], v68 offset:2240
	ds_read_b128 v[144:147], v156
	ds_read_b128 v[148:151], v156 offset:64
	ds_read_b128 v[152:155], v156 offset:2176
	ds_read_b128 v[156:159], v156 offset:2240
	s_add_u32 s42, s42, 0xb0000
	s_addc_u32 s43, s43, 0
	s_mov_b32 m0, s29
	v_lshl_add_u64 v[220:221], s[42:43], 0, v[208:209]
	ds_read_b128 v[160:163], v241 offset:34816
	ds_read_b128 v[164:167], v241 offset:34880
	ds_read_b128 v[168:171], v241 offset:36992
	ds_read_b128 v[172:175], v241 offset:37056
	ds_read_b128 v[176:179], v241 offset:39168
	ds_read_b128 v[180:183], v241 offset:39232
	ds_read_b128 v[184:187], v241 offset:41344
	ds_read_b128 v[188:191], v241 offset:41408
	global_load_lds_dwordx4 v[220:221], off
	v_lshl_add_u64 v[220:221], s[42:43], 0, v[210:211]
	s_mov_b32 m0, s56
	s_nop 0
	global_load_lds_dwordx4 v[220:221], off
	s_waitcnt vmcnt(8)
	s_waitcnt lgkmcnt(0)
	s_barrier
	s_setprio 1
	s_waitcnt lgkmcnt(0)
	v_mfma_f32_16x16x32_bf16 v[132:135], v[48:51], v[160:163], v[132:135]
	v_mfma_f32_16x16x32_bf16 v[128:131], v[64:67], v[160:163], v[128:131]
	v_mfma_f32_16x16x32_bf16 v[124:127], v[48:51], v[168:171], v[124:127]
	v_mfma_f32_16x16x32_bf16 v[120:123], v[64:67], v[168:171], v[120:123]
	v_mfma_f32_16x16x32_bf16 v[108:111], v[48:51], v[176:179], v[108:111]
	v_mfma_f32_16x16x32_bf16 v[104:107], v[64:67], v[176:179], v[104:107]
	v_mfma_f32_16x16x32_bf16 v[92:95], v[48:51], v[184:187], v[92:95]
	v_mfma_f32_16x16x32_bf16 v[88:91], v[64:67], v[184:187], v[88:91]
	v_mfma_f32_16x16x32_bf16 v[132:135], v[52:55], v[164:167], v[132:135]
	v_mfma_f32_16x16x32_bf16 v[128:131], v[68:71], v[164:167], v[128:131]
	v_mfma_f32_16x16x32_bf16 v[124:127], v[52:55], v[172:175], v[124:127]
	v_mfma_f32_16x16x32_bf16 v[120:123], v[68:71], v[172:175], v[120:123]
	v_mfma_f32_16x16x32_bf16 v[108:111], v[52:55], v[180:183], v[108:111]
	v_mfma_f32_16x16x32_bf16 v[104:107], v[68:71], v[180:183], v[104:107]
	v_mfma_f32_16x16x32_bf16 v[92:95], v[52:55], v[188:191], v[92:95]
	v_mfma_f32_16x16x32_bf16 v[88:91], v[68:71], v[188:191], v[88:91]
	v_mfma_f32_16x16x32_bf16 v[140:143], v[144:147], v[160:163], v[140:143]
	v_mfma_f32_16x16x32_bf16 v[136:139], v[152:155], v[160:163], v[136:139]
	v_mfma_f32_16x16x32_bf16 v[116:119], v[144:147], v[168:171], v[116:119]
	v_mfma_f32_16x16x32_bf16 v[112:115], v[152:155], v[168:171], v[112:115]
	v_mfma_f32_16x16x32_bf16 v[100:103], v[144:147], v[176:179], v[100:103]
	v_mfma_f32_16x16x32_bf16 v[96:99], v[152:155], v[176:179], v[96:99]
	v_mfma_f32_16x16x32_bf16 v[84:87], v[144:147], v[184:187], v[84:87]
	v_mfma_f32_16x16x32_bf16 v[80:83], v[152:155], v[184:187], v[80:83]
	v_mfma_f32_16x16x32_bf16 v[140:143], v[148:151], v[164:167], v[140:143]
	v_mfma_f32_16x16x32_bf16 v[136:139], v[156:159], v[164:167], v[136:139]
	v_mfma_f32_16x16x32_bf16 v[116:119], v[148:151], v[172:175], v[116:119]
	v_mfma_f32_16x16x32_bf16 v[112:115], v[156:159], v[172:175], v[112:115]
	v_mfma_f32_16x16x32_bf16 v[100:103], v[148:151], v[180:183], v[100:103]
	v_mfma_f32_16x16x32_bf16 v[96:99], v[156:159], v[180:183], v[96:99]
	v_mfma_f32_16x16x32_bf16 v[84:87], v[148:151], v[188:191], v[84:87]
	v_mfma_f32_16x16x32_bf16 v[80:83], v[156:159], v[188:191], v[80:83]
	s_setprio 0
	s_barrier
; #define PG8_STAGE(bufoff, gbase, voff) do { _Pragma("unroll") for (int _i = 0; _i < 2; ++_i) \
;         __builtin_amdgcn_global_load_lds((const unsigned*)((const char*)(gbase) + (voff)[_i]), (PG8_LAS unsigned*)(lds + (bufoff) + ldsw + _i * (8 * USTR)), 16, 0, 0); } while (0)
; #define PG8_LDA(dst, b, h) do { _Pragma("unroll") for (int m = 0; m < 4; ++m) _Pragma("unroll") for (int k = 0; k < 2; ++k) dst[m][k] = *(const PG8_LAS bf16x8*)(lds + PG8_SA(b, h) + aoff + m * (2 * USTR) + k * 64); } while (0)
; #define PG8_MMA(ai, bj, At, Bt) do { __builtin_amdgcn_s_setprio(1); _Pragma("unroll") for (int m = 0; m < 4; ++m) _Pragma("unroll") for (int n = 0; n < 2; ++n) _Pragma("unroll") for (int k = 0; k < 2; ++k) \
;         acc[ai][bj][m][n] = __builtin_amdgcn_mfma_f32_16x16x32_bf16(Bt[n][k], At[m][k], acc[ai][bj][m][n], 0, 0, 0); __builtin_amdgcn_s_setprio(0); } while (0)
; #define PG8_WAIT_V(n) asm volatile("s_waitcnt vmcnt(" #n ")" ::: "memory")
; #define PG8_WAIT_L(n) asm volatile("s_waitcnt lgkmcnt(" #n ")" ::: "memory")
; #define PG8_BAR __builtin_amdgcn_s_barrier()
; #define PG8_SCHED __builtin_amdgcn_sched_barrier(0)
; template <class Epi, class Sched, bool ALIGN_EPI, bool SP2>
; __device__ __forceinline__ void gemm_phase(PG8_LAS unsigned char* lds, const Gemm g, const Sched& S, const Epi& E, int wid) {
;     ...
;             PG8_LDA(At, 1, 1); PG8_STAGE(PG8_SB(1, 0), b3, voffB); PG8_STAGE(PG8_SB(1, 1), b3 + hstepB, voffB); PG8_STAGE(PG8_SA(1, 0), a3, voffA);
;             PG8_WAIT_V(8); PG8_WAIT_L(0); PG8_BAR; PG8_MMA(1, 0, At, B0); PG8_MMA(1, 1, At, B1); PG8_BAR; PG8_SCHED;
	s_add_i32 s42, s69, s33
	v_lshl_add_u64 v[198:199], v[198:199], 0, s[6:7]
	s_mov_b32 m0, s42
	ds_read_b128 v[160:163], v241 offset:52224
	ds_read_b128 v[164:167], v241 offset:52288
	ds_read_b128 v[168:171], v241 offset:54400
	ds_read_b128 v[172:175], v241 offset:54464
	ds_read_b128 v[176:179], v241 offset:56576
	ds_read_b128 v[180:183], v241 offset:56640
	ds_read_b128 v[184:187], v241 offset:58752
	ds_read_b128 v[188:191], v241 offset:58816
	global_load_lds_dwordx4 v[198:199], off
	s_add_i32 m0, s42, 0x2200
	s_add_u32 s40, s40, 0xb0080
	v_lshl_add_u64 v[198:199], v[200:201], 0, s[6:7]
	s_addc_u32 s41, s41, 0
	s_add_i32 s42, s74, s33
	global_load_lds_dwordx4 v[198:199], off
	v_lshl_add_u64 v[198:199], s[40:41], 0, v[208:209]
	s_mov_b32 m0, s42
	s_nop 0
	global_load_lds_dwordx4 v[198:199], off
	v_lshl_add_u64 v[198:199], s[40:41], 0, v[210:211]
	s_add_i32 m0, s42, 0x2200
	s_nop 0
	global_load_lds_dwordx4 v[198:199], off
	v_lshl_add_u64 v[198:199], v[216:217], 0, s[6:7]
	s_mov_b32 m0, s57
	s_nop 0
	global_load_lds_dwordx4 v[198:199], off
	v_lshl_add_u64 v[198:199], v[218:219], 0, s[6:7]
	s_mov_b32 m0, s70
	s_nop 0
	global_load_lds_dwordx4 v[198:199], off
	s_waitcnt vmcnt(8)
	s_waitcnt lgkmcnt(0)
	s_barrier
	s_setprio 1
	s_waitcnt lgkmcnt(0)
	v_mfma_f32_16x16x32_bf16 v[76:79], v[48:51], v[160:163], v[76:79]
	v_mfma_f32_16x16x32_bf16 v[72:75], v[64:67], v[160:163], v[72:75]
	v_mfma_f32_16x16x32_bf16 v[60:63], v[48:51], v[168:171], v[60:63]
	v_mfma_f32_16x16x32_bf16 v[56:59], v[64:67], v[168:171], v[56:59]
	v_mfma_f32_16x16x32_bf16 v[24:27], v[48:51], v[176:179], v[24:27]
	v_mfma_f32_16x16x32_bf16 v[28:31], v[64:67], v[176:179], v[28:31]
	v_mfma_f32_16x16x32_bf16 v[8:11], v[48:51], v[184:187], v[8:11]
	v_mfma_f32_16x16x32_bf16 v[12:15], v[64:67], v[184:187], v[12:15]
	v_mfma_f32_16x16x32_bf16 v[76:79], v[52:55], v[164:167], v[76:79]
	v_mfma_f32_16x16x32_bf16 v[72:75], v[68:71], v[164:167], v[72:75]
	v_mfma_f32_16x16x32_bf16 v[60:63], v[52:55], v[172:175], v[60:63]
	v_mfma_f32_16x16x32_bf16 v[56:59], v[68:71], v[172:175], v[56:59]
	v_mfma_f32_16x16x32_bf16 v[24:27], v[52:55], v[180:183], v[24:27]
	v_mfma_f32_16x16x32_bf16 v[28:31], v[68:71], v[180:183], v[28:31]
	v_mfma_f32_16x16x32_bf16 v[8:11], v[52:55], v[188:191], v[8:11]
	v_mfma_f32_16x16x32_bf16 v[12:15], v[68:71], v[188:191], v[12:15]
	v_mfma_f32_16x16x32_bf16 v[40:43], v[144:147], v[160:163], v[40:43]
	v_mfma_f32_16x16x32_bf16 v[68:71], v[148:151], v[164:167], v[40:43]
	v_mfma_f32_16x16x32_bf16 v[40:43], v[152:155], v[160:163], v[44:47]
	v_mfma_f32_16x16x32_bf16 v[36:39], v[144:147], v[168:171], v[36:39]
	v_mfma_f32_16x16x32_bf16 v[32:35], v[152:155], v[168:171], v[32:35]
	v_mfma_f32_16x16x32_bf16 v[20:23], v[144:147], v[176:179], v[20:23]
	v_mfma_f32_16x16x32_bf16 v[16:19], v[152:155], v[176:179], v[16:19]
	v_mfma_f32_16x16x32_bf16 v[4:7], v[144:147], v[184:187], v[4:7]
	v_mfma_f32_16x16x32_bf16 v[0:3], v[152:155], v[184:187], v[0:3]
	v_mfma_f32_16x16x32_bf16 v[64:67], v[156:159], v[164:167], v[40:43]
	v_mfma_f32_16x16x32_bf16 v[36:39], v[148:151], v[172:175], v[36:39]
	v_mfma_f32_16x16x32_bf16 v[32:35], v[156:159], v[172:175], v[32:35]
	v_mfma_f32_16x16x32_bf16 v[20:23], v[148:151], v[180:183], v[20:23]
	v_mfma_f32_16x16x32_bf16 v[16:19], v[156:159], v[180:183], v[16:19]
	v_mfma_f32_16x16x32_bf16 v[4:7], v[148:151], v[188:191], v[4:7]
	v_mfma_f32_16x16x32_bf16 v[0:3], v[156:159], v[188:191], v[0:3]
	s_setprio 0
	s_barrier
	s_add_i32 s68, s68, 2
	s_add_u32 s38, s38, 0x100
	s_addc_u32 s39, s39, 0
	s_add_u32 s26, s26, 0x100
	s_addc_u32 s27, s27, 0
	s_cmp_gt_u32 s68, 41
	s_cbranch_scc0 .LBB0_290
	s_and_b64 vcc, exec, s[20:21]
	s_cbranch_vccz .LBB0_293
	s_barrier

; #define PG8_STAGE(bufoff, gbase, voff) do { _Pragma("unroll") for (int _i = 0; _i < 2; ++_i) \
;         __builtin_amdgcn_global_load_lds((const unsigned*)((const char*)(gbase) + (voff)[_i]), (PG8_LAS unsigned*)(lds + (bufoff) + ldsw + _i * (8 * USTR)), 16, 0, 0); } while (0)
; #define PG8_LDA(dst, b, h) do { _Pragma("unroll") for (int m = 0; m < 4; ++m) _Pragma("unroll") for (int k = 0; k < 2; ++k) dst[m][k] = *(const PG8_LAS bf16x8*)(lds + PG8_SA(b, h) + aoff + m * (2 * USTR) + k * 64); } while (0)
; #define PG8_LDB(dst, b, h) do { _Pragma("unroll") for (int n = 0; n < 2; ++n) _Pragma("unroll") for (int k = 0; k < 2; ++k) dst[n][k] = *(const PG8_LAS bf16x8*)(lds + PG8_SB(b, h) + boff + n * (2 * USTR) + k * 64); } while (0)
; #define PG8_MMA(ai, bj, At, Bt) do { __builtin_amdgcn_s_setprio(1); _Pragma("unroll") for (int m = 0; m < 4; ++m) _Pragma("unroll") for (int n = 0; n < 2; ++n) _Pragma("unroll") for (int k = 0; k < 2; ++k) \
;         acc[ai][bj][m][n] = __builtin_amdgcn_mfma_f32_16x16x32_bf16(Bt[n][k], At[m][k], acc[ai][bj][m][n], 0, 0, 0); __builtin_amdgcn_s_setprio(0); } while (0)
; #define PG8_WAIT_V(n) asm volatile("s_waitcnt vmcnt(" #n ")" ::: "memory")
; #define PG8_WAIT_L(n) asm volatile("s_waitcnt lgkmcnt(" #n ")" ::: "memory")
; #define PG8_BAR __builtin_amdgcn_s_barrier()
; #define PG8_SCHED __builtin_amdgcn_sched_barrier(0)
; template <class Epi, class Sched, bool ALIGN_EPI, bool SP2>
; __device__ __forceinline__ void gemm_phase(PG8_LAS unsigned char* lds, const Gemm g, const Sched& S, const Epi& E, int wid) {
;     ...
;             PG8_LDB(B0, 0, 0); PG8_LDB(B1, 0, 1); PG8_SCHED; PG8_LDA(At, 0, 0); PG8_STAGE(PG8_SA(1, 1), a1 + hstepA, voffA);
;             PG8_WAIT_V(8); PG8_WAIT_L(0); PG8_BAR; PG8_MMA(0, 0, At, B0); PG8_MMA(0, 1, At, B1); PG8_BAR; PG8_SCHED;
;             PG8_LDA(At, 0, 1); PG8_STAGE(PG8_SB(0, 0), b2, voffB); PG8_STAGE(PG8_SB(0, 1), b2 + hstepB, voffB); PG8_STAGE(PG8_SA(0, 0), a2, voffA);
;             PG8_WAIT_V(8); PG8_WAIT_L(0); PG8_BAR; PG8_MMA(1, 0, At, B0); PG8_MMA(1, 1, At, B1); PG8_BAR; PG8_SCHED;
.LBB0_373:
	s_add_u32 s70, s38, 0xfffc0080
	s_addc_u32 s71, s39, -1
	s_and_b64 s[68:69], s[68:69], exec
	s_cselect_b32 s71, s26, s71
	s_cselect_b32 s70, s27, s70
	s_cselect_b32 s69, s41, s75
	s_cselect_b32 s68, s73, s74
	s_add_i32 s77, 0, 0x11000
	v_add_u32_e32 v94, s77, v161
	s_add_i32 s89, 0, 0x15400
	ds_read_b128 v[86:89], v94
	ds_read_b128 v[90:93], v94 offset:64
	ds_read_b128 v[164:167], v94 offset:2176
	ds_read_b128 v[168:171], v94 offset:2240
	v_add_u32_e32 v94, s89, v161
	ds_read_b128 v[172:175], v94
	ds_read_b128 v[176:179], v94 offset:64
	ds_read_b128 v[180:183], v94 offset:2176
	ds_read_b128 v[184:187], v94 offset:2240
	v_lshl_add_u64 v[94:95], s[38:39], 0, v[154:155]
	s_add_i32 m0, s0, 0xcc00
	ds_read_b128 v[188:191], v163
	ds_read_b128 v[208:211], v163 offset:64
	ds_read_b128 v[212:215], v163 offset:2176
	ds_read_b128 v[216:219], v163 offset:2240
	ds_read_b128 v[220:223], v163 offset:4352
	ds_read_b128 v[224:227], v163 offset:4416
	ds_read_b128 v[228:231], v163 offset:6528
	ds_read_b128 v[242:245], v163 offset:6592
	global_load_lds_dwordx4 v[94:95], off
	v_lshl_add_u64 v[94:95], s[38:39], 0, v[156:157]
	s_add_i32 m0, s0, 0xee00
	s_nop 0
	global_load_lds_dwordx4 v[94:95], off
	s_waitcnt vmcnt(8)
	s_waitcnt lgkmcnt(0)
	s_barrier
	s_setprio 1
	s_waitcnt lgkmcnt(0)
	v_mfma_f32_16x16x32_bf16 v[140:143], v[86:89], v[188:191], v[140:143]
	v_mfma_f32_16x16x32_bf16 v[136:139], v[164:167], v[188:191], v[136:139]
	v_mfma_f32_16x16x32_bf16 v[124:127], v[86:89], v[212:215], v[124:127]
	v_mfma_f32_16x16x32_bf16 v[120:123], v[164:167], v[212:215], v[120:123]
	v_mfma_f32_16x16x32_bf16 v[108:111], v[86:89], v[220:223], v[108:111]
	v_mfma_f32_16x16x32_bf16 v[104:107], v[164:167], v[220:223], v[104:107]
	v_mfma_f32_16x16x32_bf16 v[76:79], v[86:89], v[228:231], v[76:79]
	v_mfma_f32_16x16x32_bf16 v[72:75], v[164:167], v[228:231], v[72:75]
	v_mfma_f32_16x16x32_bf16 v[140:143], v[90:93], v[208:211], v[140:143]
	v_mfma_f32_16x16x32_bf16 v[136:139], v[168:171], v[208:211], v[136:139]
	v_mfma_f32_16x16x32_bf16 v[124:127], v[90:93], v[216:219], v[124:127]
	v_mfma_f32_16x16x32_bf16 v[120:123], v[168:171], v[216:219], v[120:123]
	v_mfma_f32_16x16x32_bf16 v[108:111], v[90:93], v[224:227], v[108:111]
	v_mfma_f32_16x16x32_bf16 v[104:107], v[168:171], v[224:227], v[104:107]
	v_mfma_f32_16x16x32_bf16 v[76:79], v[90:93], v[242:245], v[76:79]
	v_mfma_f32_16x16x32_bf16 v[72:75], v[168:171], v[242:245], v[72:75]
	v_mfma_f32_16x16x32_bf16 v[132:135], v[172:175], v[188:191], v[132:135]
	v_mfma_f32_16x16x32_bf16 v[128:131], v[180:183], v[188:191], v[128:131]
	v_mfma_f32_16x16x32_bf16 v[116:119], v[172:175], v[212:215], v[116:119]
	v_mfma_f32_16x16x32_bf16 v[112:115], v[180:183], v[212:215], v[112:115]
	v_mfma_f32_16x16x32_bf16 v[100:103], v[172:175], v[220:223], v[100:103]
	v_mfma_f32_16x16x32_bf16 v[94:97], v[180:183], v[220:223], v[96:99]
	v_mfma_f32_16x16x32_bf16 v[68:71], v[172:175], v[228:231], v[68:71]
	v_mfma_f32_16x16x32_bf16 v[64:67], v[180:183], v[228:231], v[64:67]
	v_mfma_f32_16x16x32_bf16 v[132:135], v[176:179], v[208:211], v[132:135]
	v_mfma_f32_16x16x32_bf16 v[128:131], v[184:187], v[208:211], v[128:131]
	v_mfma_f32_16x16x32_bf16 v[116:119], v[176:179], v[216:219], v[116:119]
	v_mfma_f32_16x16x32_bf16 v[112:115], v[184:187], v[216:219], v[112:115]
	v_mfma_f32_16x16x32_bf16 v[100:103], v[176:179], v[224:227], v[100:103]
	v_mfma_f32_16x16x32_bf16 v[94:97], v[184:187], v[224:227], v[94:97]
	v_mfma_f32_16x16x32_bf16 v[68:71], v[176:179], v[242:245], v[68:71]
	v_mfma_f32_16x16x32_bf16 v[64:67], v[184:187], v[242:245], v[64:67]
	s_setprio 0
	s_barrier
	s_add_i32 s77, s77, s33
	v_lshl_add_u64 v[158:159], s[68:69], 0, v[192:193]
	s_mov_b32 m0, s77
	ds_read_b128 v[188:191], v163 offset:17408
	ds_read_b128 v[208:211], v163 offset:17472
	ds_read_b128 v[212:215], v163 offset:19584
	ds_read_b128 v[216:219], v163 offset:19648
	ds_read_b128 v[220:223], v163 offset:21760
	ds_read_b128 v[224:227], v163 offset:21824
	ds_read_b128 v[228:231], v163 offset:23936
	ds_read_b128 v[242:245], v163 offset:24000
	global_load_lds_dwordx4 v[158:159], off
	s_add_i32 m0, s77, 0x2200
	s_add_u32 s78, s68, 0x40000
	v_lshl_add_u64 v[198:199], s[68:69], 0, v[144:145]
	s_addc_u32 s79, s69, 0
	s_add_i32 s77, s89, s33
	global_load_lds_dwordx4 v[198:199], off
	v_lshl_add_u64 v[98:99], s[78:79], 0, v[192:193]
	s_mov_b32 m0, s77
	v_lshl_add_u64 v[200:201], s[70:71], 0, v[148:149]
	global_load_lds_dwordx4 v[98:99], off
	v_lshl_add_u64 v[98:99], s[78:79], 0, v[144:145]
	s_add_i32 m0, s77, 0x2200
	v_lshl_add_u64 v[232:233], s[70:71], 0, v[146:147]
	global_load_lds_dwordx4 v[98:99], off
	s_mov_b32 m0, s0
	s_nop 0
	global_load_lds_dwordx4 v[200:201], off
	s_mov_b32 m0, s5
	s_nop 0
	global_load_lds_dwordx4 v[232:233], off
	s_waitcnt vmcnt(8)
	s_waitcnt lgkmcnt(0)
	s_barrier
; #define PG8_STAGE(bufoff, gbase, voff) do { _Pragma("unroll") for (int _i = 0; _i < 2; ++_i) \
;         __builtin_amdgcn_global_load_lds((const unsigned*)((const char*)(gbase) + (voff)[_i]), (PG8_LAS unsigned*)(lds + (bufoff) + ldsw + _i * (8 * USTR)), 16, 0, 0); } while (0)
; #define PG8_LDA(dst, b, h) do { _Pragma("unroll") for (int m = 0; m < 4; ++m) _Pragma("unroll") for (int k = 0; k < 2; ++k) dst[m][k] = *(const PG8_LAS bf16x8*)(lds + PG8_SA(b, h) + aoff + m * (2 * USTR) + k * 64); } while (0)
; #define PG8_LDB(dst, b, h) do { _Pragma("unroll") for (int n = 0; n < 2; ++n) _Pragma("unroll") for (int k = 0; k < 2; ++k) dst[n][k] = *(const PG8_LAS bf16x8*)(lds + PG8_SB(b, h) + boff + n * (2 * USTR) + k * 64); } while (0)
; #define PG8_MMA(ai, bj, At, Bt) do { __builtin_amdgcn_s_setprio(1); _Pragma("unroll") for (int m = 0; m < 4; ++m) _Pragma("unroll") for (int n = 0; n < 2; ++n) _Pragma("unroll") for (int k = 0; k < 2; ++k) \
;         acc[ai][bj][m][n] = __builtin_amdgcn_mfma_f32_16x16x32_bf16(Bt[n][k], At[m][k], acc[ai][bj][m][n], 0, 0, 0); __builtin_amdgcn_s_setprio(0); } while (0)
; #define PG8_WAIT_V(n) asm volatile("s_waitcnt vmcnt(" #n ")" ::: "memory")
; #define PG8_WAIT_L(n) asm volatile("s_waitcnt lgkmcnt(" #n ")" ::: "memory")
; #define PG8_BAR __builtin_amdgcn_s_barrier()
; #define PG8_SCHED __builtin_amdgcn_sched_barrier(0)
; template <class Epi, class Sched, bool ALIGN_EPI, bool SP2>
; __device__ __forceinline__ void gemm_phase(PG8_LAS unsigned char* lds, const Gemm g, const Sched& S, const Epi& E, int wid) {
;     ...
;             PG8_WAIT_V(8); PG8_WAIT_L(0); PG8_BAR; PG8_MMA(1, 0, At, B0); PG8_MMA(1, 1, At, B1); PG8_BAR; PG8_SCHED;
;             PG8_LDB(B0, 1, 0); PG8_LDB(B1, 1, 1); PG8_SCHED; PG8_LDA(At, 1, 0); PG8_STAGE(PG8_SA(0, 1), a2 + hstepA, voffA);
;             PG8_WAIT_V(8); PG8_WAIT_L(0); PG8_BAR; PG8_MMA(0, 0, At, B0); PG8_MMA(0, 1, At, B1); PG8_BAR; PG8_SCHED;
	s_setprio 1
	s_waitcnt lgkmcnt(0)
	v_mfma_f32_16x16x32_bf16 v[60:63], v[86:89], v[188:191], v[60:63]
	v_mfma_f32_16x16x32_bf16 v[56:59], v[164:167], v[188:191], v[56:59]
	v_mfma_f32_16x16x32_bf16 v[44:47], v[86:89], v[212:215], v[44:47]
	v_mfma_f32_16x16x32_bf16 v[40:43], v[164:167], v[212:215], v[40:43]
	v_mfma_f32_16x16x32_bf16 v[28:31], v[86:89], v[220:223], v[28:31]
	v_mfma_f32_16x16x32_bf16 v[24:27], v[164:167], v[220:223], v[24:27]
	v_mfma_f32_16x16x32_bf16 v[12:15], v[86:89], v[228:231], v[12:15]
	v_mfma_f32_16x16x32_bf16 v[8:11], v[164:167], v[228:231], v[8:11]
	v_mfma_f32_16x16x32_bf16 v[60:63], v[90:93], v[208:211], v[60:63]
	v_mfma_f32_16x16x32_bf16 v[56:59], v[168:171], v[208:211], v[56:59]
	v_mfma_f32_16x16x32_bf16 v[44:47], v[90:93], v[216:219], v[44:47]
	v_mfma_f32_16x16x32_bf16 v[40:43], v[168:171], v[216:219], v[40:43]
	v_mfma_f32_16x16x32_bf16 v[28:31], v[90:93], v[224:227], v[28:31]
	v_mfma_f32_16x16x32_bf16 v[24:27], v[168:171], v[224:227], v[24:27]
	v_mfma_f32_16x16x32_bf16 v[12:15], v[90:93], v[242:245], v[12:15]
	v_mfma_f32_16x16x32_bf16 v[8:11], v[168:171], v[242:245], v[8:11]
	v_mfma_f32_16x16x32_bf16 v[52:55], v[172:175], v[188:191], v[52:55]
	v_mfma_f32_16x16x32_bf16 v[48:51], v[180:183], v[188:191], v[48:51]
	v_mfma_f32_16x16x32_bf16 v[36:39], v[172:175], v[212:215], v[36:39]
	v_mfma_f32_16x16x32_bf16 v[32:35], v[180:183], v[212:215], v[32:35]
	v_mfma_f32_16x16x32_bf16 v[20:23], v[172:175], v[220:223], v[20:23]
	v_mfma_f32_16x16x32_bf16 v[16:19], v[180:183], v[220:223], v[16:19]
	v_mfma_f32_16x16x32_bf16 v[4:7], v[172:175], v[228:231], v[4:7]
	v_mfma_f32_16x16x32_bf16 v[0:3], v[180:183], v[228:231], v[0:3]
	v_mfma_f32_16x16x32_bf16 v[52:55], v[176:179], v[208:211], v[52:55]
	v_mfma_f32_16x16x32_bf16 v[48:51], v[184:187], v[208:211], v[48:51]
	v_mfma_f32_16x16x32_bf16 v[36:39], v[176:179], v[216:219], v[36:39]
	v_mfma_f32_16x16x32_bf16 v[32:35], v[184:187], v[216:219], v[32:35]
	v_mfma_f32_16x16x32_bf16 v[20:23], v[176:179], v[224:227], v[20:23]
	v_mfma_f32_16x16x32_bf16 v[16:19], v[184:187], v[224:227], v[16:19]
	v_mfma_f32_16x16x32_bf16 v[4:7], v[176:179], v[242:245], v[4:7]
	v_mfma_f32_16x16x32_bf16 v[0:3], v[184:187], v[242:245], v[0:3]
	s_setprio 0
	s_barrier
	s_add_i32 s77, 0, 0x19800
	v_add_u32_e32 v98, s77, v161
	s_add_i32 s78, 0, 0x1dc00
	ds_read_b128 v[86:89], v98
	ds_read_b128 v[90:93], v98 offset:64
	ds_read_b128 v[164:167], v98 offset:2176
	ds_read_b128 v[168:171], v98 offset:2240
	v_add_u32_e32 v98, s78, v161
	ds_read_b128 v[172:175], v98
	ds_read_b128 v[176:179], v98 offset:64
	ds_read_b128 v[180:183], v98 offset:2176
	ds_read_b128 v[184:187], v98 offset:2240
	s_add_u32 s70, s70, 0x40000
	s_addc_u32 s71, s71, 0
	s_mov_b32 m0, s10
	v_lshl_add_u64 v[98:99], s[70:71], 0, v[148:149]
	ds_read_b128 v[188:191], v163 offset:34816
	ds_read_b128 v[208:211], v163 offset:34880
	ds_read_b128 v[212:215], v163 offset:36992
	ds_read_b128 v[216:219], v163 offset:37056
	ds_read_b128 v[220:223], v163 offset:39168
	ds_read_b128 v[224:227], v163 offset:39232
	ds_read_b128 v[228:231], v163 offset:41344
	ds_read_b128 v[242:245], v163 offset:41408
	global_load_lds_dwordx4 v[98:99], off
	v_lshl_add_u64 v[98:99], s[70:71], 0, v[146:147]
	s_mov_b32 m0, s29
	s_nop 0
	global_load_lds_dwordx4 v[98:99], off
	s_waitcnt vmcnt(8)
	s_waitcnt lgkmcnt(0)
	s_barrier
	s_setprio 1
	s_waitcnt lgkmcnt(0)
	v_mfma_f32_16x16x32_bf16 v[140:143], v[86:89], v[188:191], v[140:143]
	v_mfma_f32_16x16x32_bf16 v[136:139], v[164:167], v[188:191], v[136:139]
	v_mfma_f32_16x16x32_bf16 v[124:127], v[86:89], v[212:215], v[124:127]
	v_mfma_f32_16x16x32_bf16 v[120:123], v[164:167], v[212:215], v[120:123]
	v_mfma_f32_16x16x32_bf16 v[108:111], v[86:89], v[220:223], v[108:111]
	v_mfma_f32_16x16x32_bf16 v[104:107], v[164:167], v[220:223], v[104:107]
	v_mfma_f32_16x16x32_bf16 v[76:79], v[86:89], v[228:231], v[76:79]
	v_mfma_f32_16x16x32_bf16 v[72:75], v[164:167], v[228:231], v[72:75]
	v_mfma_f32_16x16x32_bf16 v[140:143], v[90:93], v[208:211], v[140:143]
	v_mfma_f32_16x16x32_bf16 v[136:139], v[168:171], v[208:211], v[136:139]
	v_mfma_f32_16x16x32_bf16 v[124:127], v[90:93], v[216:219], v[124:127]
	v_mfma_f32_16x16x32_bf16 v[120:123], v[168:171], v[216:219], v[120:123]
	v_mfma_f32_16x16x32_bf16 v[108:111], v[90:93], v[224:227], v[108:111]
	v_mfma_f32_16x16x32_bf16 v[104:107], v[168:171], v[224:227], v[104:107]
	v_mfma_f32_16x16x32_bf16 v[76:79], v[90:93], v[242:245], v[76:79]
	v_mfma_f32_16x16x32_bf16 v[72:75], v[168:171], v[242:245], v[72:75]
	v_mfma_f32_16x16x32_bf16 v[132:135], v[172:175], v[188:191], v[132:135]
	v_mfma_f32_16x16x32_bf16 v[128:131], v[180:183], v[188:191], v[128:131]
	v_mfma_f32_16x16x32_bf16 v[116:119], v[172:175], v[212:215], v[116:119]
	v_mfma_f32_16x16x32_bf16 v[112:115], v[180:183], v[212:215], v[112:115]
	v_mfma_f32_16x16x32_bf16 v[98:101], v[172:175], v[220:223], v[100:103]
	v_mfma_f32_16x16x32_bf16 v[94:97], v[180:183], v[220:223], v[94:97]
	v_mfma_f32_16x16x32_bf16 v[68:71], v[172:175], v[228:231], v[68:71]
	v_mfma_f32_16x16x32_bf16 v[64:67], v[180:183], v[228:231], v[64:67]
	v_mfma_f32_16x16x32_bf16 v[132:135], v[176:179], v[208:211], v[132:135]
	v_mfma_f32_16x16x32_bf16 v[128:131], v[184:187], v[208:211], v[128:131]
	v_mfma_f32_16x16x32_bf16 v[116:119], v[176:179], v[216:219], v[116:119]
	v_mfma_f32_16x16x32_bf16 v[112:115], v[184:187], v[216:219], v[112:115]
	v_mfma_f32_16x16x32_bf16 v[100:103], v[176:179], v[224:227], v[98:101]
	v_mfma_f32_16x16x32_bf16 v[96:99], v[184:187], v[224:227], v[94:97]
	v_mfma_f32_16x16x32_bf16 v[68:71], v[176:179], v[242:245], v[68:71]
	v_mfma_f32_16x16x32_bf16 v[64:67], v[184:187], v[242:245], v[64:67]
	s_setprio 0
	s_barrier
; #define PG8_STAGE(bufoff, gbase, voff) do { _Pragma("unroll") for (int _i = 0; _i < 2; ++_i) \
;         __builtin_amdgcn_global_load_lds((const unsigned*)((const char*)(gbase) + (voff)[_i]), (PG8_LAS unsigned*)(lds + (bufoff) + ldsw + _i * (8 * USTR)), 16, 0, 0); } while (0)
; #define PG8_LDA(dst, b, h) do { _Pragma("unroll") for (int m = 0; m < 4; ++m) _Pragma("unroll") for (int k = 0; k < 2; ++k) dst[m][k] = *(const PG8_LAS bf16x8*)(lds + PG8_SA(b, h) + aoff + m * (2 * USTR) + k * 64); } while (0)
; #define PG8_MMA(ai, bj, At, Bt) do { __builtin_amdgcn_s_setprio(1); _Pragma("unroll") for (int m = 0; m < 4; ++m) _Pragma("unroll") for (int n = 0; n < 2; ++n) _Pragma("unroll") for (int k = 0; k < 2; ++k) \
;         acc[ai][bj][m][n] = __builtin_amdgcn_mfma_f32_16x16x32_bf16(Bt[n][k], At[m][k], acc[ai][bj][m][n], 0, 0, 0); __builtin_amdgcn_s_setprio(0); } while (0)
; #define PG8_WAIT_V(n) asm volatile("s_waitcnt vmcnt(" #n ")" ::: "memory")
; #define PG8_WAIT_L(n) asm volatile("s_waitcnt lgkmcnt(" #n ")" ::: "memory")
; #define PG8_BAR __builtin_amdgcn_s_barrier()
; #define PG8_SCHED __builtin_amdgcn_sched_barrier(0)
; template <class Epi, class Sched, bool ALIGN_EPI, bool SP2>
; __device__ __forceinline__ void gemm_phase(PG8_LAS unsigned char* lds, const Gemm g, const Sched& S, const Epi& E, int wid) {
;     ...
;             PG8_LDA(At, 1, 1); PG8_STAGE(PG8_SB(1, 0), b3, voffB); PG8_STAGE(PG8_SB(1, 1), b3 + hstepB, voffB); PG8_STAGE(PG8_SA(1, 0), a3, voffA);
;             PG8_WAIT_V(8); PG8_WAIT_L(0); PG8_BAR; PG8_MMA(1, 0, At, B0); PG8_MMA(1, 1, At, B1); PG8_BAR; PG8_SCHED;
	s_add_i32 s70, s77, s33
	v_lshl_add_u64 v[94:95], v[158:159], 0, s[6:7]
	s_mov_b32 m0, s70
	ds_read_b128 v[188:191], v163 offset:52224
	ds_read_b128 v[208:211], v163 offset:52288
	ds_read_b128 v[212:215], v163 offset:54400
	ds_read_b128 v[216:219], v163 offset:54464
	ds_read_b128 v[220:223], v163 offset:56576
	ds_read_b128 v[224:227], v163 offset:56640
	ds_read_b128 v[228:231], v163 offset:58752
	ds_read_b128 v[242:245], v163 offset:58816
	global_load_lds_dwordx4 v[94:95], off
	s_add_i32 m0, s70, 0x2200
	s_add_u32 s68, s68, 0x40080
	v_lshl_add_u64 v[94:95], v[198:199], 0, s[6:7]
	s_addc_u32 s69, s69, 0
	s_add_i32 s70, s78, s33
	global_load_lds_dwordx4 v[94:95], off
	v_lshl_add_u64 v[94:95], s[68:69], 0, v[192:193]
	s_mov_b32 m0, s70
	s_nop 0
	global_load_lds_dwordx4 v[94:95], off
	v_lshl_add_u64 v[94:95], s[68:69], 0, v[144:145]
	s_add_i32 m0, s70, 0x2200
	s_nop 0
	global_load_lds_dwordx4 v[94:95], off
	v_lshl_add_u64 v[94:95], v[200:201], 0, s[6:7]
	s_mov_b32 m0, s56
	s_nop 0
	global_load_lds_dwordx4 v[94:95], off
	v_lshl_add_u64 v[94:95], v[232:233], 0, s[6:7]
	s_mov_b32 m0, s57
	s_nop 0
	global_load_lds_dwordx4 v[94:95], off
	s_waitcnt vmcnt(8)
	s_waitcnt lgkmcnt(0)
	s_barrier
	s_setprio 1
	s_waitcnt lgkmcnt(0)
	v_mfma_f32_16x16x32_bf16 v[60:63], v[86:89], v[188:191], v[60:63]
	v_mfma_f32_16x16x32_bf16 v[56:59], v[164:167], v[188:191], v[56:59]
	v_mfma_f32_16x16x32_bf16 v[44:47], v[86:89], v[212:215], v[44:47]
	v_mfma_f32_16x16x32_bf16 v[40:43], v[164:167], v[212:215], v[40:43]
	v_mfma_f32_16x16x32_bf16 v[28:31], v[86:89], v[220:223], v[28:31]
	v_mfma_f32_16x16x32_bf16 v[24:27], v[164:167], v[220:223], v[24:27]
	v_mfma_f32_16x16x32_bf16 v[12:15], v[86:89], v[228:231], v[12:15]
	v_mfma_f32_16x16x32_bf16 v[8:11], v[164:167], v[228:231], v[8:11]
	v_mfma_f32_16x16x32_bf16 v[60:63], v[90:93], v[208:211], v[60:63]
	v_mfma_f32_16x16x32_bf16 v[56:59], v[168:171], v[208:211], v[56:59]
	v_mfma_f32_16x16x32_bf16 v[44:47], v[90:93], v[216:219], v[44:47]
	v_mfma_f32_16x16x32_bf16 v[40:43], v[168:171], v[216:219], v[40:43]
	v_mfma_f32_16x16x32_bf16 v[28:31], v[90:93], v[224:227], v[28:31]
	v_mfma_f32_16x16x32_bf16 v[24:27], v[168:171], v[224:227], v[24:27]
	v_mfma_f32_16x16x32_bf16 v[12:15], v[90:93], v[242:245], v[12:15]
	v_mfma_f32_16x16x32_bf16 v[8:11], v[168:171], v[242:245], v[8:11]
	v_mfma_f32_16x16x32_bf16 v[52:55], v[172:175], v[188:191], v[52:55]
	v_mfma_f32_16x16x32_bf16 v[48:51], v[180:183], v[188:191], v[48:51]
	v_mfma_f32_16x16x32_bf16 v[36:39], v[172:175], v[212:215], v[36:39]
	v_mfma_f32_16x16x32_bf16 v[32:35], v[180:183], v[212:215], v[32:35]
	v_mfma_f32_16x16x32_bf16 v[20:23], v[172:175], v[220:223], v[20:23]
	v_mfma_f32_16x16x32_bf16 v[16:19], v[180:183], v[220:223], v[16:19]
	v_mfma_f32_16x16x32_bf16 v[4:7], v[172:175], v[228:231], v[4:7]
	v_mfma_f32_16x16x32_bf16 v[0:3], v[180:183], v[228:231], v[0:3]
	v_mfma_f32_16x16x32_bf16 v[52:55], v[176:179], v[208:211], v[52:55]
	v_mfma_f32_16x16x32_bf16 v[48:51], v[184:187], v[208:211], v[48:51]
	v_mfma_f32_16x16x32_bf16 v[36:39], v[176:179], v[216:219], v[36:39]
	v_mfma_f32_16x16x32_bf16 v[32:35], v[184:187], v[216:219], v[32:35]
	v_mfma_f32_16x16x32_bf16 v[20:23], v[176:179], v[224:227], v[20:23]
	v_mfma_f32_16x16x32_bf16 v[16:19], v[184:187], v[224:227], v[16:19]
	v_mfma_f32_16x16x32_bf16 v[4:7], v[176:179], v[242:245], v[4:7]
	v_mfma_f32_16x16x32_bf16 v[0:3], v[184:187], v[242:245], v[0:3]
	s_setprio 0
	s_barrier
	s_add_i32 s76, s76, 2
	s_add_u32 s38, s38, 0x100
	s_addc_u32 s39, s39, 0
	s_add_u32 s74, s74, 0x100
	s_addc_u32 s75, s75, 0
	s_cmp_gt_u32 s76, 13
	s_cbranch_scc1 .LBB0_377

; #define PG8_STAGE(bufoff, gbase, voff) do { _Pragma("unroll") for (int _i = 0; _i < 2; ++_i) \
;         __builtin_amdgcn_global_load_lds((const unsigned*)((const char*)(gbase) + (voff)[_i]), (PG8_LAS unsigned*)(lds + (bufoff) + ldsw + _i * (8 * USTR)), 16, 0, 0); } while (0)
; #define PG8_LDA(dst, b, h) do { _Pragma("unroll") for (int m = 0; m < 4; ++m) _Pragma("unroll") for (int k = 0; k < 2; ++k) dst[m][k] = *(const PG8_LAS bf16x8*)(lds + PG8_SA(b, h) + aoff + m * (2 * USTR) + k * 64); } while (0)
; #define PG8_LDB(dst, b, h) do { _Pragma("unroll") for (int n = 0; n < 2; ++n) _Pragma("unroll") for (int k = 0; k < 2; ++k) dst[n][k] = *(const PG8_LAS bf16x8*)(lds + PG8_SB(b, h) + boff + n * (2 * USTR) + k * 64); } while (0)
; #define PG8_MMA(ai, bj, At, Bt) do { __builtin_amdgcn_s_setprio(1); _Pragma("unroll") for (int m = 0; m < 4; ++m) _Pragma("unroll") for (int n = 0; n < 2; ++n) _Pragma("unroll") for (int k = 0; k < 2; ++k) \
;         acc[ai][bj][m][n] = __builtin_amdgcn_mfma_f32_16x16x32_bf16(Bt[n][k], At[m][k], acc[ai][bj][m][n], 0, 0, 0); __builtin_amdgcn_s_setprio(0); } while (0)
; #define PG8_WAIT_V(n) asm volatile("s_waitcnt vmcnt(" #n ")" ::: "memory")
; #define PG8_WAIT_L(n) asm volatile("s_waitcnt lgkmcnt(" #n ")" ::: "memory")
; #define PG8_BAR __builtin_amdgcn_s_barrier()
; #define PG8_SCHED __builtin_amdgcn_sched_barrier(0)
; template <class Epi, class Sched, bool ALIGN_EPI, bool SP2>
; __device__ __forceinline__ void gemm_phase(PG8_LAS unsigned char* lds, const Gemm g, const Sched& S, const Epi& E, int wid) {
;     ...
;             PG8_LDB(B0, 0, 0); PG8_LDB(B1, 0, 1); PG8_SCHED; PG8_LDA(At, 0, 0); PG8_STAGE(PG8_SA(1, 1), a1 + hstepA, voffA);
;             PG8_WAIT_V(8); PG8_WAIT_L(0); PG8_BAR; PG8_MMA(0, 0, At, B0); PG8_MMA(0, 1, At, B1); PG8_BAR; PG8_SCHED;
;             PG8_LDA(At, 0, 1); PG8_STAGE(PG8_SB(0, 0), b2, voffB); PG8_STAGE(PG8_SB(0, 1), b2 + hstepB, voffB); PG8_STAGE(PG8_SA(0, 0), a2, voffA);
;             PG8_WAIT_V(8); PG8_WAIT_L(0); PG8_BAR; PG8_MMA(1, 0, At, B0); PG8_MMA(1, 1, At, B1); PG8_BAR; PG8_SCHED;
.LBB0_393:
	s_add_u32 s42, s38, 0xfffc0080
	s_addc_u32 s43, s39, -1
	s_and_b64 s[40:41], s[40:41], exec
	s_cselect_b32 s43, s10, s43
	s_cselect_b32 s42, s44, s42
	s_cselect_b32 s41, s45, s70
	s_cselect_b32 s40, s69, s23
	s_add_i32 s73, 0, 0x11000
	v_add_u32_e32 v30, s73, v197
	s_add_i32 vcc_lo, 0, 0x15400
	ds_read_b128 v[22:25], v30
	ds_read_b128 v[26:29], v30 offset:64
	ds_read_b128 v[158:161], v30 offset:2176
	ds_read_b128 v[162:165], v30 offset:2240
	v_add_u32_e32 v30, vcc_lo, v197
	ds_read_b128 v[166:169], v30
	ds_read_b128 v[170:173], v30 offset:64
	ds_read_b128 v[174:177], v30 offset:2176
	ds_read_b128 v[178:181], v30 offset:2240
	v_lshl_add_u64 v[30:31], s[38:39], 0, v[154:155]
	s_add_i32 m0, s95, 0xcc00
	ds_read_b128 v[182:185], v210
	ds_read_b128 v[186:189], v210 offset:64
	ds_read_b128 v[212:215], v210 offset:2176
	ds_read_b128 v[216:219], v210 offset:2240
	ds_read_b128 v[220:223], v210 offset:4352
	ds_read_b128 v[224:227], v210 offset:4416
	ds_read_b128 v[228:231], v210 offset:6528
	ds_read_b128 v[242:245], v210 offset:6592
	global_load_lds_dwordx4 v[30:31], off
	v_lshl_add_u64 v[30:31], s[38:39], 0, v[156:157]
	s_add_i32 m0, s95, 0xee00
	s_nop 0
	global_load_lds_dwordx4 v[30:31], off
	s_waitcnt vmcnt(8)
	s_waitcnt lgkmcnt(0)
	s_barrier
	s_setprio 1
	s_waitcnt lgkmcnt(0)
	v_mfma_f32_16x16x32_bf16 v[140:143], v[22:25], v[182:185], v[140:143]
	v_mfma_f32_16x16x32_bf16 v[136:139], v[158:161], v[182:185], v[136:139]
	v_mfma_f32_16x16x32_bf16 v[124:127], v[22:25], v[212:215], v[124:127]
	v_mfma_f32_16x16x32_bf16 v[120:123], v[158:161], v[212:215], v[120:123]
	v_mfma_f32_16x16x32_bf16 v[108:111], v[22:25], v[220:223], v[108:111]
	v_mfma_f32_16x16x32_bf16 v[104:107], v[158:161], v[220:223], v[104:107]
	v_mfma_f32_16x16x32_bf16 v[92:95], v[22:25], v[228:231], v[92:95]
	v_mfma_f32_16x16x32_bf16 v[88:91], v[158:161], v[228:231], v[88:91]
	v_mfma_f32_16x16x32_bf16 v[140:143], v[26:29], v[186:189], v[140:143]
	v_mfma_f32_16x16x32_bf16 v[136:139], v[162:165], v[186:189], v[136:139]
	v_mfma_f32_16x16x32_bf16 v[124:127], v[26:29], v[216:219], v[124:127]
	v_mfma_f32_16x16x32_bf16 v[120:123], v[162:165], v[216:219], v[120:123]
	v_mfma_f32_16x16x32_bf16 v[108:111], v[26:29], v[224:227], v[108:111]
	v_mfma_f32_16x16x32_bf16 v[104:107], v[162:165], v[224:227], v[104:107]
	v_mfma_f32_16x16x32_bf16 v[92:95], v[26:29], v[242:245], v[92:95]
	v_mfma_f32_16x16x32_bf16 v[88:91], v[162:165], v[242:245], v[88:91]
	v_mfma_f32_16x16x32_bf16 v[132:135], v[166:169], v[182:185], v[132:135]
	v_mfma_f32_16x16x32_bf16 v[128:131], v[174:177], v[182:185], v[128:131]
	v_mfma_f32_16x16x32_bf16 v[116:119], v[166:169], v[212:215], v[116:119]
	v_mfma_f32_16x16x32_bf16 v[112:115], v[174:177], v[212:215], v[112:115]
	v_mfma_f32_16x16x32_bf16 v[100:103], v[166:169], v[220:223], v[100:103]
	v_mfma_f32_16x16x32_bf16 v[96:99], v[174:177], v[220:223], v[96:99]
	v_mfma_f32_16x16x32_bf16 v[84:87], v[166:169], v[228:231], v[84:87]
	v_mfma_f32_16x16x32_bf16 v[80:83], v[174:177], v[228:231], v[80:83]
	v_mfma_f32_16x16x32_bf16 v[132:135], v[170:173], v[186:189], v[132:135]
	v_mfma_f32_16x16x32_bf16 v[128:131], v[178:181], v[186:189], v[128:131]
	v_mfma_f32_16x16x32_bf16 v[116:119], v[170:173], v[216:219], v[116:119]
	v_mfma_f32_16x16x32_bf16 v[112:115], v[178:181], v[216:219], v[112:115]
	v_mfma_f32_16x16x32_bf16 v[100:103], v[170:173], v[224:227], v[100:103]
	v_mfma_f32_16x16x32_bf16 v[96:99], v[178:181], v[224:227], v[96:99]
	v_mfma_f32_16x16x32_bf16 v[84:87], v[170:173], v[242:245], v[84:87]
	v_mfma_f32_16x16x32_bf16 v[80:83], v[178:181], v[242:245], v[80:83]
	s_setprio 0
	s_barrier
	s_add_i32 s73, s73, s33
	v_lshl_add_u64 v[190:191], s[40:41], 0, v[192:193]
	s_mov_b32 m0, s73
	ds_read_b128 v[182:185], v210 offset:17408
	ds_read_b128 v[186:189], v210 offset:17472
	ds_read_b128 v[212:215], v210 offset:19584
	ds_read_b128 v[216:219], v210 offset:19648
	ds_read_b128 v[220:223], v210 offset:21760
	ds_read_b128 v[224:227], v210 offset:21824
	ds_read_b128 v[228:231], v210 offset:23936
	ds_read_b128 v[242:245], v210 offset:24000
	global_load_lds_dwordx4 v[190:191], off
	s_add_i32 m0, s73, 0x2200
	s_add_u32 s76, s40, 0x40000
	v_lshl_add_u64 v[198:199], s[40:41], 0, v[146:147]
	s_addc_u32 s77, s41, 0
	s_add_i32 s73, vcc_lo, s33
	global_load_lds_dwordx4 v[198:199], off
	v_lshl_add_u64 v[30:31], s[76:77], 0, v[192:193]
	s_mov_b32 m0, s73
	v_lshl_add_u64 v[200:201], s[42:43], 0, v[150:151]
	global_load_lds_dwordx4 v[30:31], off
	v_lshl_add_u64 v[30:31], s[76:77], 0, v[146:147]
	s_add_i32 m0, s73, 0x2200
	v_lshl_add_u64 v[208:209], s[42:43], 0, v[148:149]
	global_load_lds_dwordx4 v[30:31], off
	s_mov_b32 m0, s95
	s_nop 0
	global_load_lds_dwordx4 v[200:201], off
	s_mov_b32 m0, s5
	s_nop 0
	global_load_lds_dwordx4 v[208:209], off
	s_waitcnt vmcnt(8)
	s_waitcnt lgkmcnt(0)
	s_barrier
; #define PG8_STAGE(bufoff, gbase, voff) do { _Pragma("unroll") for (int _i = 0; _i < 2; ++_i) \
;         __builtin_amdgcn_global_load_lds((const unsigned*)((const char*)(gbase) + (voff)[_i]), (PG8_LAS unsigned*)(lds + (bufoff) + ldsw + _i * (8 * USTR)), 16, 0, 0); } while (0)
; #define PG8_LDA(dst, b, h) do { _Pragma("unroll") for (int m = 0; m < 4; ++m) _Pragma("unroll") for (int k = 0; k < 2; ++k) dst[m][k] = *(const PG8_LAS bf16x8*)(lds + PG8_SA(b, h) + aoff + m * (2 * USTR) + k * 64); } while (0)
; #define PG8_LDB(dst, b, h) do { _Pragma("unroll") for (int n = 0; n < 2; ++n) _Pragma("unroll") for (int k = 0; k < 2; ++k) dst[n][k] = *(const PG8_LAS bf16x8*)(lds + PG8_SB(b, h) + boff + n * (2 * USTR) + k * 64); } while (0)
; #define PG8_MMA(ai, bj, At, Bt) do { __builtin_amdgcn_s_setprio(1); _Pragma("unroll") for (int m = 0; m < 4; ++m) _Pragma("unroll") for (int n = 0; n < 2; ++n) _Pragma("unroll") for (int k = 0; k < 2; ++k) \
;         acc[ai][bj][m][n] = __builtin_amdgcn_mfma_f32_16x16x32_bf16(Bt[n][k], At[m][k], acc[ai][bj][m][n], 0, 0, 0); __builtin_amdgcn_s_setprio(0); } while (0)
; #define PG8_WAIT_V(n) asm volatile("s_waitcnt vmcnt(" #n ")" ::: "memory")
; #define PG8_WAIT_L(n) asm volatile("s_waitcnt lgkmcnt(" #n ")" ::: "memory")
; #define PG8_BAR __builtin_amdgcn_s_barrier()
; #define PG8_SCHED __builtin_amdgcn_sched_barrier(0)
; template <class Epi, class Sched, bool ALIGN_EPI, bool SP2>
; __device__ __forceinline__ void gemm_phase(PG8_LAS unsigned char* lds, const Gemm g, const Sched& S, const Epi& E, int wid) {
;     ...
;             PG8_WAIT_V(8); PG8_WAIT_L(0); PG8_BAR; PG8_MMA(1, 0, At, B0); PG8_MMA(1, 1, At, B1); PG8_BAR; PG8_SCHED;
;             PG8_LDB(B0, 1, 0); PG8_LDB(B1, 1, 1); PG8_SCHED; PG8_LDA(At, 1, 0); PG8_STAGE(PG8_SA(0, 1), a2 + hstepA, voffA);
;             PG8_WAIT_V(8); PG8_WAIT_L(0); PG8_BAR; PG8_MMA(0, 0, At, B0); PG8_MMA(0, 1, At, B1); PG8_BAR; PG8_SCHED;
	s_setprio 1
	s_waitcnt lgkmcnt(0)
	v_mfma_f32_16x16x32_bf16 v[76:79], v[22:25], v[182:185], v[76:79]
	v_mfma_f32_16x16x32_bf16 v[72:75], v[158:161], v[182:185], v[72:75]
	v_mfma_f32_16x16x32_bf16 v[60:63], v[22:25], v[212:215], v[60:63]
	v_mfma_f32_16x16x32_bf16 v[56:59], v[158:161], v[212:215], v[56:59]
	v_mfma_f32_16x16x32_bf16 v[44:47], v[22:25], v[220:223], v[44:47]
	v_mfma_f32_16x16x32_bf16 v[40:43], v[158:161], v[220:223], v[40:43]
	v_mfma_f32_16x16x32_bf16 v[12:15], v[22:25], v[228:231], v[12:15]
	v_mfma_f32_16x16x32_bf16 v[8:11], v[158:161], v[228:231], v[8:11]
	v_mfma_f32_16x16x32_bf16 v[76:79], v[26:29], v[186:189], v[76:79]
	v_mfma_f32_16x16x32_bf16 v[72:75], v[162:165], v[186:189], v[72:75]
	v_mfma_f32_16x16x32_bf16 v[60:63], v[26:29], v[216:219], v[60:63]
	v_mfma_f32_16x16x32_bf16 v[56:59], v[162:165], v[216:219], v[56:59]
	v_mfma_f32_16x16x32_bf16 v[44:47], v[26:29], v[224:227], v[44:47]
	v_mfma_f32_16x16x32_bf16 v[40:43], v[162:165], v[224:227], v[40:43]
	v_mfma_f32_16x16x32_bf16 v[12:15], v[26:29], v[242:245], v[12:15]
	v_mfma_f32_16x16x32_bf16 v[8:11], v[162:165], v[242:245], v[8:11]
	v_mfma_f32_16x16x32_bf16 v[52:55], v[166:169], v[212:215], v[52:55]
	v_mfma_f32_16x16x32_bf16 v[48:51], v[174:177], v[212:215], v[48:51]
	v_mfma_f32_16x16x32_bf16 v[36:39], v[166:169], v[220:223], v[36:39]
	v_mfma_f32_16x16x32_bf16 v[30:33], v[174:177], v[220:223], v[32:35]
	v_mfma_f32_16x16x32_bf16 v[4:7], v[166:169], v[228:231], v[4:7]
	v_mfma_f32_16x16x32_bf16 v[0:3], v[174:177], v[228:231], v[0:3]
	v_mfma_f32_16x16x32_bf16 v[22:25], v[166:169], v[182:185], v[68:71]
	v_mfma_f32_16x16x32_bf16 v[26:29], v[174:177], v[182:185], v[64:67]
	v_mfma_f32_16x16x32_bf16 v[52:55], v[170:173], v[216:219], v[52:55]
	v_mfma_f32_16x16x32_bf16 v[48:51], v[178:181], v[216:219], v[48:51]
	v_mfma_f32_16x16x32_bf16 v[36:39], v[170:173], v[224:227], v[36:39]
	v_mfma_f32_16x16x32_bf16 v[30:33], v[178:181], v[224:227], v[30:33]
	v_mfma_f32_16x16x32_bf16 v[4:7], v[170:173], v[242:245], v[4:7]
	v_mfma_f32_16x16x32_bf16 v[0:3], v[178:181], v[242:245], v[0:3]
	v_mfma_f32_16x16x32_bf16 v[22:25], v[170:173], v[186:189], v[22:25]
	v_mfma_f32_16x16x32_bf16 v[26:29], v[178:181], v[186:189], v[26:29]
	s_setprio 0
	s_barrier
	s_add_i32 s73, 0, 0x19800
	v_add_u32_e32 v34, s73, v197
	s_add_i32 s76, 0, 0x1dc00
	ds_read_b128 v[64:67], v34
	ds_read_b128 v[68:71], v34 offset:64
	ds_read_b128 v[158:161], v34 offset:2176
	ds_read_b128 v[162:165], v34 offset:2240
	v_add_u32_e32 v34, s76, v197
	ds_read_b128 v[166:169], v34
	ds_read_b128 v[170:173], v34 offset:64
	ds_read_b128 v[174:177], v34 offset:2176
	ds_read_b128 v[178:181], v34 offset:2240
	s_add_u32 s42, s42, 0x40000
	s_addc_u32 s43, s43, 0
	s_mov_b32 m0, s56
	v_lshl_add_u64 v[34:35], s[42:43], 0, v[150:151]
	ds_read_b128 v[182:185], v210 offset:34816
	ds_read_b128 v[186:189], v210 offset:34880
	ds_read_b128 v[212:215], v210 offset:36992
	ds_read_b128 v[216:219], v210 offset:37056
	ds_read_b128 v[220:223], v210 offset:39168
	ds_read_b128 v[224:227], v210 offset:39232
	ds_read_b128 v[228:231], v210 offset:41344
	ds_read_b128 v[242:245], v210 offset:41408
	global_load_lds_dwordx4 v[34:35], off
	v_lshl_add_u64 v[34:35], s[42:43], 0, v[148:149]
	s_mov_b32 m0, s57
	s_nop 0
	global_load_lds_dwordx4 v[34:35], off
	s_waitcnt vmcnt(8)
	s_waitcnt lgkmcnt(0)
	s_barrier
	s_setprio 1
	s_waitcnt lgkmcnt(0)
	v_mfma_f32_16x16x32_bf16 v[140:143], v[64:67], v[182:185], v[140:143]
	v_mfma_f32_16x16x32_bf16 v[136:139], v[158:161], v[182:185], v[136:139]
	v_mfma_f32_16x16x32_bf16 v[124:127], v[64:67], v[212:215], v[124:127]
	v_mfma_f32_16x16x32_bf16 v[120:123], v[158:161], v[212:215], v[120:123]
	v_mfma_f32_16x16x32_bf16 v[108:111], v[64:67], v[220:223], v[108:111]
	v_mfma_f32_16x16x32_bf16 v[104:107], v[158:161], v[220:223], v[104:107]
	v_mfma_f32_16x16x32_bf16 v[92:95], v[64:67], v[228:231], v[92:95]
	v_mfma_f32_16x16x32_bf16 v[88:91], v[158:161], v[228:231], v[88:91]
	v_mfma_f32_16x16x32_bf16 v[140:143], v[68:71], v[186:189], v[140:143]
	v_mfma_f32_16x16x32_bf16 v[136:139], v[162:165], v[186:189], v[136:139]
	v_mfma_f32_16x16x32_bf16 v[124:127], v[68:71], v[216:219], v[124:127]
	v_mfma_f32_16x16x32_bf16 v[120:123], v[162:165], v[216:219], v[120:123]
	v_mfma_f32_16x16x32_bf16 v[108:111], v[68:71], v[224:227], v[108:111]
	v_mfma_f32_16x16x32_bf16 v[104:107], v[162:165], v[224:227], v[104:107]
	v_mfma_f32_16x16x32_bf16 v[92:95], v[68:71], v[242:245], v[92:95]
	v_mfma_f32_16x16x32_bf16 v[88:91], v[162:165], v[242:245], v[88:91]
	v_mfma_f32_16x16x32_bf16 v[132:135], v[166:169], v[182:185], v[132:135]
	v_mfma_f32_16x16x32_bf16 v[128:131], v[174:177], v[182:185], v[128:131]
	v_mfma_f32_16x16x32_bf16 v[116:119], v[166:169], v[212:215], v[116:119]
	v_mfma_f32_16x16x32_bf16 v[112:115], v[174:177], v[212:215], v[112:115]
	v_mfma_f32_16x16x32_bf16 v[100:103], v[166:169], v[220:223], v[100:103]
	v_mfma_f32_16x16x32_bf16 v[96:99], v[174:177], v[220:223], v[96:99]
	v_mfma_f32_16x16x32_bf16 v[84:87], v[166:169], v[228:231], v[84:87]
	v_mfma_f32_16x16x32_bf16 v[80:83], v[174:177], v[228:231], v[80:83]
	v_mfma_f32_16x16x32_bf16 v[132:135], v[170:173], v[186:189], v[132:135]
	v_mfma_f32_16x16x32_bf16 v[128:131], v[178:181], v[186:189], v[128:131]
	v_mfma_f32_16x16x32_bf16 v[116:119], v[170:173], v[216:219], v[116:119]
	v_mfma_f32_16x16x32_bf16 v[112:115], v[178:181], v[216:219], v[112:115]
	v_mfma_f32_16x16x32_bf16 v[100:103], v[170:173], v[224:227], v[100:103]
	v_mfma_f32_16x16x32_bf16 v[96:99], v[178:181], v[224:227], v[96:99]
	v_mfma_f32_16x16x32_bf16 v[84:87], v[170:173], v[242:245], v[84:87]
	v_mfma_f32_16x16x32_bf16 v[80:83], v[178:181], v[242:245], v[80:83]
	s_setprio 0
	s_barrier
; #define PG8_STAGE(bufoff, gbase, voff) do { _Pragma("unroll") for (int _i = 0; _i < 2; ++_i) \
;         __builtin_amdgcn_global_load_lds((const unsigned*)((const char*)(gbase) + (voff)[_i]), (PG8_LAS unsigned*)(lds + (bufoff) + ldsw + _i * (8 * USTR)), 16, 0, 0); } while (0)
; #define PG8_LDA(dst, b, h) do { _Pragma("unroll") for (int m = 0; m < 4; ++m) _Pragma("unroll") for (int k = 0; k < 2; ++k) dst[m][k] = *(const PG8_LAS bf16x8*)(lds + PG8_SA(b, h) + aoff + m * (2 * USTR) + k * 64); } while (0)
; #define PG8_MMA(ai, bj, At, Bt) do { __builtin_amdgcn_s_setprio(1); _Pragma("unroll") for (int m = 0; m < 4; ++m) _Pragma("unroll") for (int n = 0; n < 2; ++n) _Pragma("unroll") for (int k = 0; k < 2; ++k) \
;         acc[ai][bj][m][n] = __builtin_amdgcn_mfma_f32_16x16x32_bf16(Bt[n][k], At[m][k], acc[ai][bj][m][n], 0, 0, 0); __builtin_amdgcn_s_setprio(0); } while (0)
; #define PG8_WAIT_V(n) asm volatile("s_waitcnt vmcnt(" #n ")" ::: "memory")
; #define PG8_WAIT_L(n) asm volatile("s_waitcnt lgkmcnt(" #n ")" ::: "memory")
; #define PG8_BAR __builtin_amdgcn_s_barrier()
; #define PG8_SCHED __builtin_amdgcn_sched_barrier(0)
; template <class Epi, class Sched, bool ALIGN_EPI, bool SP2>
; __device__ __forceinline__ void gemm_phase(PG8_LAS unsigned char* lds, const Gemm g, const Sched& S, const Epi& E, int wid) {
;     ...
;             PG8_LDA(At, 1, 1); PG8_STAGE(PG8_SB(1, 0), b3, voffB); PG8_STAGE(PG8_SB(1, 1), b3 + hstepB, voffB); PG8_STAGE(PG8_SA(1, 0), a3, voffA);
;             PG8_WAIT_V(8); PG8_WAIT_L(0); PG8_BAR; PG8_MMA(1, 0, At, B0); PG8_MMA(1, 1, At, B1); PG8_BAR; PG8_SCHED;
	s_add_i32 s42, s73, s33
	v_lshl_add_u64 v[34:35], v[190:191], 0, s[6:7]
	s_mov_b32 m0, s42
	ds_read_b128 v[182:185], v210 offset:52224
	ds_read_b128 v[186:189], v210 offset:52288
	ds_read_b128 v[212:215], v210 offset:54400
	ds_read_b128 v[216:219], v210 offset:54464
	ds_read_b128 v[220:223], v210 offset:56576
	ds_read_b128 v[224:227], v210 offset:56640
	ds_read_b128 v[228:231], v210 offset:58752
	ds_read_b128 v[242:245], v210 offset:58816
	global_load_lds_dwordx4 v[34:35], off
	s_add_i32 m0, s42, 0x2200
	s_add_u32 s40, s40, 0x40080
	v_lshl_add_u64 v[34:35], v[198:199], 0, s[6:7]
	s_addc_u32 s41, s41, 0
	s_add_i32 s42, s76, s33
	global_load_lds_dwordx4 v[34:35], off
	v_lshl_add_u64 v[34:35], s[40:41], 0, v[192:193]
	s_mov_b32 m0, s42
	s_nop 0
	global_load_lds_dwordx4 v[34:35], off
	v_lshl_add_u64 v[34:35], s[40:41], 0, v[146:147]
	s_add_i32 m0, s42, 0x2200
	s_nop 0
	global_load_lds_dwordx4 v[34:35], off
	v_lshl_add_u64 v[34:35], v[200:201], 0, s[6:7]
	s_mov_b32 m0, s29
	s_nop 0
	global_load_lds_dwordx4 v[34:35], off
	v_lshl_add_u64 v[34:35], v[208:209], 0, s[6:7]
	s_mov_b32 m0, s0
	s_nop 0
	global_load_lds_dwordx4 v[34:35], off
	s_waitcnt vmcnt(8)
	s_waitcnt lgkmcnt(0)
	s_barrier
	s_setprio 1
	s_waitcnt lgkmcnt(0)
	v_mfma_f32_16x16x32_bf16 v[76:79], v[64:67], v[182:185], v[76:79]
	v_mfma_f32_16x16x32_bf16 v[72:75], v[158:161], v[182:185], v[72:75]
	v_mfma_f32_16x16x32_bf16 v[60:63], v[64:67], v[212:215], v[60:63]
	v_mfma_f32_16x16x32_bf16 v[56:59], v[158:161], v[212:215], v[56:59]
	v_mfma_f32_16x16x32_bf16 v[44:47], v[64:67], v[220:223], v[44:47]
	v_mfma_f32_16x16x32_bf16 v[40:43], v[158:161], v[220:223], v[40:43]
	v_mfma_f32_16x16x32_bf16 v[12:15], v[64:67], v[228:231], v[12:15]
	v_mfma_f32_16x16x32_bf16 v[8:11], v[158:161], v[228:231], v[8:11]
	v_mfma_f32_16x16x32_bf16 v[76:79], v[68:71], v[186:189], v[76:79]
	v_mfma_f32_16x16x32_bf16 v[72:75], v[162:165], v[186:189], v[72:75]
	v_mfma_f32_16x16x32_bf16 v[60:63], v[68:71], v[216:219], v[60:63]
	v_mfma_f32_16x16x32_bf16 v[56:59], v[162:165], v[216:219], v[56:59]
	v_mfma_f32_16x16x32_bf16 v[44:47], v[68:71], v[224:227], v[44:47]
	v_mfma_f32_16x16x32_bf16 v[40:43], v[162:165], v[224:227], v[40:43]
	v_mfma_f32_16x16x32_bf16 v[12:15], v[68:71], v[242:245], v[12:15]
	v_mfma_f32_16x16x32_bf16 v[8:11], v[162:165], v[242:245], v[8:11]
	v_mfma_f32_16x16x32_bf16 v[22:25], v[166:169], v[182:185], v[22:25]
	v_mfma_f32_16x16x32_bf16 v[68:71], v[170:173], v[186:189], v[22:25]
	v_mfma_f32_16x16x32_bf16 v[22:25], v[174:177], v[182:185], v[26:29]
	v_mfma_f32_16x16x32_bf16 v[64:67], v[178:181], v[186:189], v[22:25]
	v_mfma_f32_16x16x32_bf16 v[22:25], v[166:169], v[212:215], v[52:55]
	v_mfma_f32_16x16x32_bf16 v[52:55], v[170:173], v[216:219], v[22:25]
	v_mfma_f32_16x16x32_bf16 v[22:25], v[174:177], v[212:215], v[48:51]
	v_mfma_f32_16x16x32_bf16 v[48:51], v[178:181], v[216:219], v[22:25]
	v_mfma_f32_16x16x32_bf16 v[22:25], v[166:169], v[220:223], v[36:39]
	v_mfma_f32_16x16x32_bf16 v[36:39], v[170:173], v[224:227], v[22:25]
	v_mfma_f32_16x16x32_bf16 v[22:25], v[174:177], v[220:223], v[30:33]
	v_mfma_f32_16x16x32_bf16 v[4:7], v[166:169], v[228:231], v[4:7]
	v_mfma_f32_16x16x32_bf16 v[0:3], v[174:177], v[228:231], v[0:3]
	v_mfma_f32_16x16x32_bf16 v[32:35], v[178:181], v[224:227], v[22:25]
	v_mfma_f32_16x16x32_bf16 v[4:7], v[170:173], v[242:245], v[4:7]
	v_mfma_f32_16x16x32_bf16 v[0:3], v[178:181], v[242:245], v[0:3]
	s_setprio 0
	s_barrier
	s_add_i32 s71, s71, 2
	s_add_u32 s38, s38, 0x100
	s_addc_u32 s39, s39, 0
	s_add_u32 s23, s23, 0x100
	s_addc_u32 s70, s70, 0
	s_cmp_gt_u32 s71, 13
	s_cbranch_scc1 .LBB0_397
